# GEMM K-loops: per-block s_setprio 1/0 toggles removed; one static priority raise for the trailing wave half (threads >= 256) for the duration of each K-loop
# baseline (speedup 1.0000x reference)
.LBB0_410:
	s_ashr_i32 s51, s50, 31
	s_lshl_b64 s[36:37], s[50:51], 20
	s_mov_b64 s[42:43], s[14:15]
	s_add_u32 s52, s42, s36
	s_addc_u32 s53, s43, s37
	s_and_b64 s[36:37], s[38:39], exec
	s_cselect_b32 s41, s53, s3
	s_cselect_b32 s42, s52, s2
	s_ashr_i32 s49, s48, 31
	s_lshl_b64 s[36:37], s[48:49], 20
	s_add_u32 s54, s17, s36
	s_addc_u32 s55, s18, s37
	s_and_b64 s[36:37], s[38:39], exec
	s_cselect_b32 s43, s55, s31
	s_cselect_b32 s44, s54, s30
	s_add_u32 s2, s2, 0x80080
	s_addc_u32 s3, s3, 0
	s_add_u32 s45, s30, 0x100
	v_mov_b32_e32 v2, 0
	s_addc_u32 s46, s31, 0
	s_mov_b32 s47, -2
	v_mov_b32_e32 v3, v2
	v_mov_b32_e32 v4, v2
	v_mov_b32_e32 v5, v2
	v_mov_b32_e32 v6, v2
	v_mov_b32_e32 v7, v2
	v_mov_b32_e32 v8, v2
	v_mov_b32_e32 v9, v2
	s_waitcnt vmcnt(0)
	v_mov_b32_e32 v18, v2
	v_mov_b32_e32 v19, v2
	s_waitcnt vmcnt(0)
	v_mov_b32_e32 v20, v2
	v_mov_b32_e32 v21, v2
	v_mov_b32_e32 v22, v2
	v_mov_b32_e32 v23, v2
	v_mov_b32_e32 v24, v2
	v_mov_b32_e32 v25, v2
	v_mov_b32_e32 v34, v2
	v_mov_b32_e32 v35, v2
	v_mov_b32_e32 v36, v2
	v_mov_b32_e32 v37, v2
	v_mov_b32_e32 v38, v2
	v_mov_b32_e32 v39, v2
	v_mov_b32_e32 v40, v2
	v_mov_b32_e32 v41, v2
	v_mov_b32_e32 v50, v2
	v_mov_b32_e32 v51, v2
	v_mov_b32_e32 v52, v2
	v_mov_b32_e32 v53, v2
	v_mov_b32_e32 v54, v2
	v_mov_b32_e32 v55, v2
	v_mov_b32_e32 v56, v2
	v_mov_b32_e32 v57, v2
	v_mov_b32_e32 v10, v2
	v_mov_b32_e32 v11, v2
	v_mov_b32_e32 v12, v2
	v_mov_b32_e32 v13, v2
	v_mov_b32_e32 v14, v2
	v_mov_b32_e32 v15, v2
	v_mov_b32_e32 v16, v2
	v_mov_b32_e32 v17, v2
	v_mov_b32_e32 v26, v2
	v_mov_b32_e32 v27, v2
	v_mov_b32_e32 v28, v2
	v_mov_b32_e32 v29, v2
	v_mov_b32_e32 v30, v2
	v_mov_b32_e32 v31, v2
	v_mov_b32_e32 v32, v2
	v_mov_b32_e32 v33, v2
	v_mov_b32_e32 v42, v2
	v_mov_b32_e32 v43, v2
	v_mov_b32_e32 v44, v2
	v_mov_b32_e32 v45, v2
	v_mov_b32_e32 v46, v2
	v_mov_b32_e32 v47, v2
	v_mov_b32_e32 v48, v2
	v_mov_b32_e32 v49, v2
	v_mov_b32_e32 v58, v2
	v_mov_b32_e32 v59, v2
	v_mov_b32_e32 v60, v2
	v_mov_b32_e32 v61, v2
	v_mov_b32_e32 v62, v2
	v_mov_b32_e32 v63, v2
	v_mov_b32_e32 v64, v2
	v_mov_b32_e32 v65, v2
	v_mov_b32_e32 v66, v2
	v_mov_b32_e32 v67, v2
	v_mov_b32_e32 v68, v2
	v_mov_b32_e32 v69, v2
	v_mov_b32_e32 v70, v2
	v_mov_b32_e32 v71, v2
	v_mov_b32_e32 v72, v2
	v_mov_b32_e32 v73, v2
	v_mov_b32_e32 v82, v2
	v_mov_b32_e32 v83, v2
	v_mov_b32_e32 v84, v2
	v_mov_b32_e32 v85, v2
	v_mov_b32_e32 v86, v2
	v_mov_b32_e32 v87, v2
	v_mov_b32_e32 v88, v2
	v_mov_b32_e32 v89, v2
	v_mov_b32_e32 v98, v2
	v_mov_b32_e32 v99, v2
	v_mov_b32_e32 v100, v2
	v_mov_b32_e32 v101, v2
	v_mov_b32_e32 v102, v2
	v_mov_b32_e32 v103, v2
	v_mov_b32_e32 v104, v2
	v_mov_b32_e32 v105, v2
	v_mov_b32_e32 v114, v2
	v_mov_b32_e32 v115, v2
	v_mov_b32_e32 v116, v2
	v_mov_b32_e32 v117, v2
	v_mov_b32_e32 v118, v2
	v_mov_b32_e32 v119, v2
	v_mov_b32_e32 v120, v2
	v_mov_b32_e32 v121, v2
	v_mov_b32_e32 v74, v2
	v_mov_b32_e32 v75, v2
	v_mov_b32_e32 v76, v2
	v_mov_b32_e32 v77, v2
	v_mov_b32_e32 v78, v2
	v_mov_b32_e32 v79, v2
	v_mov_b32_e32 v80, v2
	v_mov_b32_e32 v81, v2
	v_mov_b32_e32 v90, v2
	v_mov_b32_e32 v91, v2
	v_mov_b32_e32 v92, v2
	v_mov_b32_e32 v93, v2
	v_mov_b32_e32 v94, v2
	v_mov_b32_e32 v95, v2
	v_mov_b32_e32 v96, v2
	v_mov_b32_e32 v97, v2
	v_mov_b32_e32 v106, v2
	v_mov_b32_e32 v107, v2
	v_mov_b32_e32 v108, v2
	v_mov_b32_e32 v109, v2
	v_mov_b32_e32 v110, v2
	v_mov_b32_e32 v111, v2
	v_mov_b32_e32 v112, v2
	v_mov_b32_e32 v113, v2
	v_mov_b32_e32 v122, v2
	v_mov_b32_e32 v123, v2
	v_mov_b32_e32 v124, v2
	v_mov_b32_e32 v125, v2
	v_mov_b32_e32 v126, v2
	v_mov_b32_e32 v127, v2
	v_mov_b32_e32 v128, v2
	v_mov_b32_e32 v129, v2
	v_readfirstlane_b32 s100, v211
	s_cmp_lt_u32 s100, 0x100
	s_cbranch_scc1 .Lpr_lead0
	s_setprio 1
.Lpr_lead0:
.LBB0_411:
	s_add_u32 s30, s2, 0xfff80080
	s_addc_u32 s31, s3, -1
	s_add_i32 s49, 0, 0x10000
	s_cmp_eq_u32 s47, 28
	s_cselect_b32 s37, s41, s31
	s_cselect_b32 s36, s42, s30
	s_cselect_b32 s31, s43, s46
	s_cselect_b32 s30, s44, s45
	s_add_i32 s51, 0, 0x14000
	v_add_u32_e32 v142, s49, v197
	v_add_u32_e32 v172, s51, v197
	ds_read_b128 v[130:133], v142
	ds_read_b128 v[134:137], v142 offset:1024
	ds_read_b128 v[138:141], v142 offset:2048
	ds_read_b128 v[142:145], v142 offset:3072
	ds_read_b128 v[160:163], v172
	ds_read_b128 v[164:167], v172 offset:1024
	ds_read_b128 v[168:171], v172 offset:2048
	ds_read_b128 v[172:175], v172 offset:3072
	v_lshl_add_u64 v[220:221], s[2:3], 0, v[156:157]
	s_add_i32 m0, s24, 0xc000
	ds_read_b128 v[176:179], v200
	ds_read_b128 v[180:183], v200 offset:1024
	ds_read_b128 v[184:187], v200 offset:2048
	ds_read_b128 v[188:191], v200 offset:3072
	ds_read_b128 v[192:195], v200 offset:4096
	ds_read_b128 v[202:205], v200 offset:5120
	ds_read_b128 v[206:209], v200 offset:6144
	ds_read_b128 v[216:219], v200 offset:7168
	global_load_lds_dwordx4 v[220:221], off
	v_lshl_add_u64 v[220:221], s[2:3], 0, v[158:159]
	s_add_i32 m0, s24, 0xe000
	s_nop 0
	global_load_lds_dwordx4 v[220:221], off
	s_waitcnt vmcnt(8)
	s_waitcnt lgkmcnt(0)
	s_barrier
	s_waitcnt lgkmcnt(0)
	v_mfma_f32_16x16x32_bf16 v[126:129], v[130:133], v[176:179], v[126:129]
	v_mfma_f32_16x16x32_bf16 v[122:125], v[138:141], v[176:179], v[122:125]
	v_mfma_f32_16x16x32_bf16 v[110:113], v[130:133], v[184:187], v[110:113]
	v_mfma_f32_16x16x32_bf16 v[106:109], v[138:141], v[184:187], v[106:109]
	v_mfma_f32_16x16x32_bf16 v[94:97], v[130:133], v[192:195], v[94:97]
	v_mfma_f32_16x16x32_bf16 v[90:93], v[138:141], v[192:195], v[90:93]
	v_mfma_f32_16x16x32_bf16 v[78:81], v[130:133], v[206:209], v[78:81]
	v_mfma_f32_16x16x32_bf16 v[74:77], v[138:141], v[206:209], v[74:77]
	v_mfma_f32_16x16x32_bf16 v[126:129], v[134:137], v[180:183], v[126:129]
	v_mfma_f32_16x16x32_bf16 v[122:125], v[142:145], v[180:183], v[122:125]
	v_mfma_f32_16x16x32_bf16 v[110:113], v[134:137], v[188:191], v[110:113]
	v_mfma_f32_16x16x32_bf16 v[106:109], v[142:145], v[188:191], v[106:109]
	v_mfma_f32_16x16x32_bf16 v[94:97], v[134:137], v[202:205], v[94:97]
	v_mfma_f32_16x16x32_bf16 v[90:93], v[142:145], v[202:205], v[90:93]
	v_mfma_f32_16x16x32_bf16 v[78:81], v[134:137], v[216:219], v[78:81]
	v_mfma_f32_16x16x32_bf16 v[74:77], v[142:145], v[216:219], v[74:77]
	v_mfma_f32_16x16x32_bf16 v[118:121], v[160:163], v[176:179], v[118:121]
	v_mfma_f32_16x16x32_bf16 v[114:117], v[168:171], v[176:179], v[114:117]
	v_mfma_f32_16x16x32_bf16 v[102:105], v[160:163], v[184:187], v[102:105]
	v_mfma_f32_16x16x32_bf16 v[98:101], v[168:171], v[184:187], v[98:101]
	v_mfma_f32_16x16x32_bf16 v[86:89], v[160:163], v[192:195], v[86:89]
	v_mfma_f32_16x16x32_bf16 v[82:85], v[168:171], v[192:195], v[82:85]
	v_mfma_f32_16x16x32_bf16 v[70:73], v[160:163], v[206:209], v[70:73]
	v_mfma_f32_16x16x32_bf16 v[66:69], v[168:171], v[206:209], v[66:69]
	v_mfma_f32_16x16x32_bf16 v[118:121], v[164:167], v[180:183], v[118:121]
	v_mfma_f32_16x16x32_bf16 v[114:117], v[172:175], v[180:183], v[114:117]
	v_mfma_f32_16x16x32_bf16 v[102:105], v[164:167], v[188:191], v[102:105]
	v_mfma_f32_16x16x32_bf16 v[98:101], v[172:175], v[188:191], v[98:101]
	v_mfma_f32_16x16x32_bf16 v[86:89], v[164:167], v[202:205], v[86:89]
	v_mfma_f32_16x16x32_bf16 v[82:85], v[172:175], v[202:205], v[82:85]
	v_mfma_f32_16x16x32_bf16 v[70:73], v[164:167], v[216:219], v[70:73]
	v_mfma_f32_16x16x32_bf16 v[66:69], v[172:175], v[216:219], v[66:69]
	s_barrier
	s_add_i32 s49, s49, s19
	v_lshl_add_u64 v[220:221], s[30:31], 0, v[0:1]
	s_mov_b32 m0, s49
	ds_read_b128 v[176:179], v200 offset:16384
	ds_read_b128 v[180:183], v200 offset:17408
	ds_read_b128 v[184:187], v200 offset:18432
	ds_read_b128 v[188:191], v200 offset:19456
	ds_read_b128 v[192:195], v200 offset:20480
	ds_read_b128 v[202:205], v200 offset:21504
	ds_read_b128 v[206:209], v200 offset:22528
	ds_read_b128 v[216:219], v200 offset:23552
	global_load_lds_dwordx4 v[220:221], off
	s_add_i32 m0, s49, 0x2000
	s_add_u32 s64, s30, 0x80000
	v_lshl_add_u64 v[222:223], s[30:31], 0, v[146:147]
	s_addc_u32 s65, s31, 0
	s_add_i32 s49, s51, s19
	global_load_lds_dwordx4 v[222:223], off
	v_lshl_add_u64 v[240:241], s[64:65], 0, v[0:1]
	s_mov_b32 m0, s49
	v_lshl_add_u64 v[242:243], s[36:37], 0, v[148:149]
	global_load_lds_dwordx4 v[240:241], off
	v_lshl_add_u64 v[240:241], s[64:65], 0, v[146:147]
	s_add_i32 m0, s49, 0x2000
	s_nop 0
	global_load_lds_dwordx4 v[240:241], off
	v_lshl_add_u64 v[240:241], s[36:37], 0, v[150:151]
	s_mov_b32 m0, s24
	s_nop 0
	global_load_lds_dwordx4 v[240:241], off
	s_mov_b32 m0, s56
	s_nop 0
	global_load_lds_dwordx4 v[242:243], off
	s_waitcnt vmcnt(8)
	s_waitcnt lgkmcnt(0)
	s_barrier
	s_waitcnt lgkmcnt(0)
	v_mfma_f32_16x16x32_bf16 v[62:65], v[130:133], v[176:179], v[62:65]
	v_mfma_f32_16x16x32_bf16 v[58:61], v[138:141], v[176:179], v[58:61]
	v_mfma_f32_16x16x32_bf16 v[46:49], v[130:133], v[184:187], v[46:49]
	v_mfma_f32_16x16x32_bf16 v[42:45], v[138:141], v[184:187], v[42:45]
	v_mfma_f32_16x16x32_bf16 v[30:33], v[130:133], v[192:195], v[30:33]
	v_mfma_f32_16x16x32_bf16 v[26:29], v[138:141], v[192:195], v[26:29]
	v_mfma_f32_16x16x32_bf16 v[14:17], v[130:133], v[206:209], v[14:17]
	v_mfma_f32_16x16x32_bf16 v[10:13], v[138:141], v[206:209], v[10:13]
	v_mfma_f32_16x16x32_bf16 v[62:65], v[134:137], v[180:183], v[62:65]
	v_mfma_f32_16x16x32_bf16 v[58:61], v[142:145], v[180:183], v[58:61]
	v_mfma_f32_16x16x32_bf16 v[46:49], v[134:137], v[188:191], v[46:49]
	v_mfma_f32_16x16x32_bf16 v[42:45], v[142:145], v[188:191], v[42:45]
	v_mfma_f32_16x16x32_bf16 v[30:33], v[134:137], v[202:205], v[30:33]
	v_mfma_f32_16x16x32_bf16 v[26:29], v[142:145], v[202:205], v[26:29]
	v_mfma_f32_16x16x32_bf16 v[14:17], v[134:137], v[216:219], v[14:17]
	v_mfma_f32_16x16x32_bf16 v[10:13], v[142:145], v[216:219], v[10:13]
	v_mfma_f32_16x16x32_bf16 v[54:57], v[160:163], v[176:179], v[54:57]
	v_mfma_f32_16x16x32_bf16 v[50:53], v[168:171], v[176:179], v[50:53]
	v_mfma_f32_16x16x32_bf16 v[38:41], v[160:163], v[184:187], v[38:41]
	v_mfma_f32_16x16x32_bf16 v[34:37], v[168:171], v[184:187], v[34:37]
	v_mfma_f32_16x16x32_bf16 v[22:25], v[160:163], v[192:195], v[22:25]
	v_mfma_f32_16x16x32_bf16 v[18:21], v[168:171], v[192:195], v[18:21]
	v_mfma_f32_16x16x32_bf16 v[6:9], v[160:163], v[206:209], v[6:9]
	v_mfma_f32_16x16x32_bf16 v[2:5], v[168:171], v[206:209], v[2:5]
	v_mfma_f32_16x16x32_bf16 v[54:57], v[164:167], v[180:183], v[54:57]
	v_mfma_f32_16x16x32_bf16 v[50:53], v[172:175], v[180:183], v[50:53]
	v_mfma_f32_16x16x32_bf16 v[38:41], v[164:167], v[188:191], v[38:41]
	v_mfma_f32_16x16x32_bf16 v[34:37], v[172:175], v[188:191], v[34:37]
	v_mfma_f32_16x16x32_bf16 v[22:25], v[164:167], v[202:205], v[22:25]
	v_mfma_f32_16x16x32_bf16 v[18:21], v[172:175], v[202:205], v[18:21]
	v_mfma_f32_16x16x32_bf16 v[6:9], v[164:167], v[216:219], v[6:9]
	v_mfma_f32_16x16x32_bf16 v[2:5], v[172:175], v[216:219], v[2:5]
	s_barrier
	s_add_i32 s49, 0, 0x18000
	s_add_i32 s51, 0, 0x1c000
	v_add_u32_e32 v142, s49, v197
	v_add_u32_e32 v172, s51, v197
	ds_read_b128 v[130:133], v142
	ds_read_b128 v[134:137], v142 offset:1024
	ds_read_b128 v[138:141], v142 offset:2048
	ds_read_b128 v[142:145], v142 offset:3072
	ds_read_b128 v[160:163], v172
	ds_read_b128 v[164:167], v172 offset:1024
	ds_read_b128 v[168:171], v172 offset:2048
	ds_read_b128 v[172:175], v172 offset:3072
	s_add_u32 s36, s36, 0x80000
	s_addc_u32 s37, s37, 0
	s_mov_b32 m0, s57
	v_lshl_add_u64 v[244:245], s[36:37], 0, v[150:151]
	ds_read_b128 v[176:179], v200 offset:32768
	ds_read_b128 v[180:183], v200 offset:33792
	ds_read_b128 v[184:187], v200 offset:34816
	ds_read_b128 v[188:191], v200 offset:35840
	ds_read_b128 v[192:195], v200 offset:36864
	ds_read_b128 v[202:205], v200 offset:37888
	ds_read_b128 v[206:209], v200 offset:38912
	ds_read_b128 v[216:219], v200 offset:39936
	global_load_lds_dwordx4 v[244:245], off
	v_lshl_add_u64 v[244:245], s[36:37], 0, v[148:149]
	s_mov_b32 m0, s58
	s_nop 0
	global_load_lds_dwordx4 v[244:245], off
	s_waitcnt vmcnt(8)
	s_waitcnt lgkmcnt(0)
	s_barrier
	s_waitcnt lgkmcnt(0)
	v_mfma_f32_16x16x32_bf16 v[126:129], v[130:133], v[176:179], v[126:129]
	v_mfma_f32_16x16x32_bf16 v[122:125], v[138:141], v[176:179], v[122:125]
	v_mfma_f32_16x16x32_bf16 v[110:113], v[130:133], v[184:187], v[110:113]
	v_mfma_f32_16x16x32_bf16 v[106:109], v[138:141], v[184:187], v[106:109]
	v_mfma_f32_16x16x32_bf16 v[94:97], v[130:133], v[192:195], v[94:97]
	v_mfma_f32_16x16x32_bf16 v[90:93], v[138:141], v[192:195], v[90:93]
	v_mfma_f32_16x16x32_bf16 v[78:81], v[130:133], v[206:209], v[78:81]
	v_mfma_f32_16x16x32_bf16 v[74:77], v[138:141], v[206:209], v[74:77]
	v_mfma_f32_16x16x32_bf16 v[126:129], v[134:137], v[180:183], v[126:129]
	v_mfma_f32_16x16x32_bf16 v[122:125], v[142:145], v[180:183], v[122:125]
	v_mfma_f32_16x16x32_bf16 v[110:113], v[134:137], v[188:191], v[110:113]
	v_mfma_f32_16x16x32_bf16 v[106:109], v[142:145], v[188:191], v[106:109]
	v_mfma_f32_16x16x32_bf16 v[94:97], v[134:137], v[202:205], v[94:97]
	v_mfma_f32_16x16x32_bf16 v[90:93], v[142:145], v[202:205], v[90:93]
	v_mfma_f32_16x16x32_bf16 v[78:81], v[134:137], v[216:219], v[78:81]
	v_mfma_f32_16x16x32_bf16 v[74:77], v[142:145], v[216:219], v[74:77]
	v_mfma_f32_16x16x32_bf16 v[118:121], v[160:163], v[176:179], v[118:121]
	v_mfma_f32_16x16x32_bf16 v[114:117], v[168:171], v[176:179], v[114:117]
	v_mfma_f32_16x16x32_bf16 v[102:105], v[160:163], v[184:187], v[102:105]
	v_mfma_f32_16x16x32_bf16 v[98:101], v[168:171], v[184:187], v[98:101]
	v_mfma_f32_16x16x32_bf16 v[86:89], v[160:163], v[192:195], v[86:89]
	v_mfma_f32_16x16x32_bf16 v[82:85], v[168:171], v[192:195], v[82:85]
	v_mfma_f32_16x16x32_bf16 v[70:73], v[160:163], v[206:209], v[70:73]
	v_mfma_f32_16x16x32_bf16 v[66:69], v[168:171], v[206:209], v[66:69]
	v_mfma_f32_16x16x32_bf16 v[118:121], v[164:167], v[180:183], v[118:121]
	v_mfma_f32_16x16x32_bf16 v[114:117], v[172:175], v[180:183], v[114:117]
	v_mfma_f32_16x16x32_bf16 v[102:105], v[164:167], v[188:191], v[102:105]
	v_mfma_f32_16x16x32_bf16 v[98:101], v[172:175], v[188:191], v[98:101]
	v_mfma_f32_16x16x32_bf16 v[86:89], v[164:167], v[202:205], v[86:89]
	v_mfma_f32_16x16x32_bf16 v[82:85], v[172:175], v[202:205], v[82:85]
	v_mfma_f32_16x16x32_bf16 v[70:73], v[164:167], v[216:219], v[70:73]
	v_mfma_f32_16x16x32_bf16 v[66:69], v[172:175], v[216:219], v[66:69]
	s_barrier
	s_add_i32 s36, s49, s19
	v_lshl_add_u64 v[220:221], v[220:221], 0, s[22:23]
	s_mov_b32 m0, s36
	ds_read_b128 v[176:179], v200 offset:49152
	ds_read_b128 v[180:183], v200 offset:50176
	ds_read_b128 v[184:187], v200 offset:51200
	ds_read_b128 v[188:191], v200 offset:52224
	ds_read_b128 v[192:195], v200 offset:53248
	ds_read_b128 v[202:205], v200 offset:54272
	ds_read_b128 v[206:209], v200 offset:55296
	ds_read_b128 v[216:219], v200 offset:56320
	global_load_lds_dwordx4 v[220:221], off
	s_add_i32 m0, s36, 0x2000
	s_add_u32 s30, s30, 0x80080
	v_lshl_add_u64 v[220:221], v[222:223], 0, s[22:23]
	s_addc_u32 s31, s31, 0
	s_add_i32 s36, s51, s19
	global_load_lds_dwordx4 v[220:221], off
	v_lshl_add_u64 v[220:221], s[30:31], 0, v[0:1]
	s_mov_b32 m0, s36
	s_nop 0
	global_load_lds_dwordx4 v[220:221], off
	v_lshl_add_u64 v[220:221], s[30:31], 0, v[146:147]
	s_add_i32 m0, s36, 0x2000
	s_nop 0
	global_load_lds_dwordx4 v[220:221], off
	v_lshl_add_u64 v[220:221], v[240:241], 0, s[22:23]
	s_mov_b32 m0, s59
	s_nop 0
	global_load_lds_dwordx4 v[220:221], off
	v_lshl_add_u64 v[220:221], v[242:243], 0, s[22:23]
	s_mov_b32 m0, s60
	s_nop 0
	global_load_lds_dwordx4 v[220:221], off
	s_waitcnt vmcnt(8)
	s_waitcnt lgkmcnt(0)
	s_barrier
	s_waitcnt lgkmcnt(0)
	v_mfma_f32_16x16x32_bf16 v[62:65], v[130:133], v[176:179], v[62:65]
	v_mfma_f32_16x16x32_bf16 v[58:61], v[138:141], v[176:179], v[58:61]
	v_mfma_f32_16x16x32_bf16 v[46:49], v[130:133], v[184:187], v[46:49]
	v_mfma_f32_16x16x32_bf16 v[42:45], v[138:141], v[184:187], v[42:45]
	v_mfma_f32_16x16x32_bf16 v[30:33], v[130:133], v[192:195], v[30:33]
	v_mfma_f32_16x16x32_bf16 v[26:29], v[138:141], v[192:195], v[26:29]
	v_mfma_f32_16x16x32_bf16 v[14:17], v[130:133], v[206:209], v[14:17]
	v_mfma_f32_16x16x32_bf16 v[10:13], v[138:141], v[206:209], v[10:13]
	v_mfma_f32_16x16x32_bf16 v[62:65], v[134:137], v[180:183], v[62:65]
	v_mfma_f32_16x16x32_bf16 v[58:61], v[142:145], v[180:183], v[58:61]
	v_mfma_f32_16x16x32_bf16 v[46:49], v[134:137], v[188:191], v[46:49]
	v_mfma_f32_16x16x32_bf16 v[42:45], v[142:145], v[188:191], v[42:45]
	v_mfma_f32_16x16x32_bf16 v[30:33], v[134:137], v[202:205], v[30:33]
	v_mfma_f32_16x16x32_bf16 v[26:29], v[142:145], v[202:205], v[26:29]
	v_mfma_f32_16x16x32_bf16 v[14:17], v[134:137], v[216:219], v[14:17]
	v_mfma_f32_16x16x32_bf16 v[10:13], v[142:145], v[216:219], v[10:13]
	v_mfma_f32_16x16x32_bf16 v[54:57], v[160:163], v[176:179], v[54:57]
	v_mfma_f32_16x16x32_bf16 v[50:53], v[168:171], v[176:179], v[50:53]
	v_mfma_f32_16x16x32_bf16 v[38:41], v[160:163], v[184:187], v[38:41]
	v_mfma_f32_16x16x32_bf16 v[34:37], v[168:171], v[184:187], v[34:37]
	v_mfma_f32_16x16x32_bf16 v[22:25], v[160:163], v[192:195], v[22:25]
	v_mfma_f32_16x16x32_bf16 v[18:21], v[168:171], v[192:195], v[18:21]
	v_mfma_f32_16x16x32_bf16 v[6:9], v[160:163], v[206:209], v[6:9]
	v_mfma_f32_16x16x32_bf16 v[2:5], v[168:171], v[206:209], v[2:5]
	v_mfma_f32_16x16x32_bf16 v[54:57], v[164:167], v[180:183], v[54:57]
	v_mfma_f32_16x16x32_bf16 v[50:53], v[172:175], v[180:183], v[50:53]
	v_mfma_f32_16x16x32_bf16 v[38:41], v[164:167], v[188:191], v[38:41]
	v_mfma_f32_16x16x32_bf16 v[34:37], v[172:175], v[188:191], v[34:37]
	v_mfma_f32_16x16x32_bf16 v[22:25], v[164:167], v[202:205], v[22:25]
	v_mfma_f32_16x16x32_bf16 v[18:21], v[172:175], v[202:205], v[18:21]
	v_mfma_f32_16x16x32_bf16 v[6:9], v[164:167], v[216:219], v[6:9]
	v_mfma_f32_16x16x32_bf16 v[2:5], v[172:175], v[216:219], v[2:5]
	s_barrier
	s_add_i32 s47, s47, 2
	s_add_u32 s2, s2, 0x100
	s_addc_u32 s3, s3, 0
	s_add_u32 s45, s45, 0x100
	s_addc_u32 s46, s46, 0
	s_cmp_gt_u32 s47, 29
	s_cbranch_scc0 .LBB0_411
	s_setprio 0
	s_and_b64 vcc, exec, s[6:7]
	s_cbranch_vccz .LBB0_414
	s_barrier

.LBB0_553:
	s_ashr_i32 s37, s36, 31
	s_lshl_b64 s[40:41], s[36:37], 20
	s_add_u32 s42, s17, s40
	s_addc_u32 s43, s18, s41
	s_and_b64 s[40:41], s[38:39], exec
	s_cselect_b32 s37, s43, s3
	s_cselect_b32 s54, s42, s2
	s_ashr_i32 s9, s8, 31
	s_lshl_b64 s[40:41], s[8:9], 20
	s_mov_b64 s[44:45], s[14:15]
	s_add_u32 s44, s44, s40
	s_addc_u32 s45, s45, s41
	s_and_b64 s[40:41], s[38:39], exec
	s_cselect_b32 s9, s45, s31
	s_cselect_b32 s55, s44, s30
	s_add_u32 s2, s2, 0x80080
	s_addc_u32 s3, s3, 0
	s_add_u32 s56, s30, 0x100
	v_mov_b32_e32 v2, 0
	s_addc_u32 s57, s31, 0
	s_mov_b32 s58, -2
	v_mov_b32_e32 v3, v2
	v_mov_b32_e32 v4, v2
	v_mov_b32_e32 v5, v2
	v_mov_b32_e32 v6, v2
	v_mov_b32_e32 v7, v2
	v_mov_b32_e32 v8, v2
	v_mov_b32_e32 v9, v2
	v_mov_b32_e32 v18, v2
	v_mov_b32_e32 v19, v2
	v_mov_b32_e32 v20, v2
	v_mov_b32_e32 v21, v2
	v_mov_b32_e32 v22, v2
	v_mov_b32_e32 v23, v2
	v_mov_b32_e32 v24, v2
	v_mov_b32_e32 v25, v2
	v_mov_b32_e32 v34, v2
	v_mov_b32_e32 v35, v2
	v_mov_b32_e32 v36, v2
	v_mov_b32_e32 v37, v2
	v_mov_b32_e32 v38, v2
	v_mov_b32_e32 v39, v2
	v_mov_b32_e32 v40, v2
	v_mov_b32_e32 v41, v2
	v_mov_b32_e32 v50, v2
	v_mov_b32_e32 v51, v2
	v_mov_b32_e32 v52, v2
	v_mov_b32_e32 v53, v2
	v_mov_b32_e32 v54, v2
	v_mov_b32_e32 v55, v2
	v_mov_b32_e32 v56, v2
	v_mov_b32_e32 v57, v2
	v_mov_b32_e32 v10, v2
	v_mov_b32_e32 v11, v2
	v_mov_b32_e32 v12, v2
	v_mov_b32_e32 v13, v2
	v_mov_b32_e32 v14, v2
	v_mov_b32_e32 v15, v2
	v_mov_b32_e32 v16, v2
	v_mov_b32_e32 v17, v2
	v_mov_b32_e32 v26, v2
	v_mov_b32_e32 v27, v2
	v_mov_b32_e32 v28, v2
	v_mov_b32_e32 v29, v2
	v_mov_b32_e32 v30, v2
	v_mov_b32_e32 v31, v2
	v_mov_b32_e32 v32, v2
	v_mov_b32_e32 v33, v2
	v_mov_b32_e32 v42, v2
	v_mov_b32_e32 v43, v2
	v_mov_b32_e32 v44, v2
	v_mov_b32_e32 v45, v2
	v_mov_b32_e32 v46, v2
	v_mov_b32_e32 v47, v2
	v_mov_b32_e32 v48, v2
	v_mov_b32_e32 v49, v2
	v_mov_b32_e32 v58, v2
	v_mov_b32_e32 v59, v2
	v_mov_b32_e32 v60, v2
	v_mov_b32_e32 v61, v2
	v_mov_b32_e32 v62, v2
	v_mov_b32_e32 v63, v2
	v_mov_b32_e32 v64, v2
	v_mov_b32_e32 v65, v2
	v_mov_b32_e32 v66, v2
	v_mov_b32_e32 v67, v2
	v_mov_b32_e32 v68, v2
	v_mov_b32_e32 v69, v2
	v_mov_b32_e32 v70, v2
	v_mov_b32_e32 v71, v2
	v_mov_b32_e32 v72, v2
	v_mov_b32_e32 v73, v2
	v_mov_b32_e32 v82, v2
	v_mov_b32_e32 v83, v2
	v_mov_b32_e32 v84, v2
	v_mov_b32_e32 v85, v2
	v_mov_b32_e32 v86, v2
	v_mov_b32_e32 v87, v2
	v_mov_b32_e32 v88, v2
	v_mov_b32_e32 v89, v2
	v_mov_b32_e32 v98, v2
	v_mov_b32_e32 v99, v2
	v_mov_b32_e32 v100, v2
	v_mov_b32_e32 v101, v2
	v_mov_b32_e32 v102, v2
	v_mov_b32_e32 v103, v2
	v_mov_b32_e32 v104, v2
	v_mov_b32_e32 v105, v2
	v_mov_b32_e32 v114, v2
	v_mov_b32_e32 v115, v2
	v_mov_b32_e32 v116, v2
	v_mov_b32_e32 v117, v2
	v_mov_b32_e32 v118, v2
	v_mov_b32_e32 v119, v2
	v_mov_b32_e32 v120, v2
	v_mov_b32_e32 v121, v2
	v_mov_b32_e32 v74, v2
	v_mov_b32_e32 v75, v2
	v_mov_b32_e32 v76, v2
	v_mov_b32_e32 v77, v2
	v_mov_b32_e32 v78, v2
	v_mov_b32_e32 v79, v2
	v_mov_b32_e32 v80, v2
	v_mov_b32_e32 v81, v2
	v_mov_b32_e32 v90, v2
	v_mov_b32_e32 v91, v2
	v_mov_b32_e32 v92, v2
	v_mov_b32_e32 v93, v2
	v_mov_b32_e32 v94, v2
	v_mov_b32_e32 v95, v2
	v_mov_b32_e32 v96, v2
	v_mov_b32_e32 v97, v2
	v_mov_b32_e32 v106, v2
	v_mov_b32_e32 v107, v2
	v_mov_b32_e32 v108, v2
	v_mov_b32_e32 v109, v2
	v_mov_b32_e32 v110, v2
	v_mov_b32_e32 v111, v2
	v_mov_b32_e32 v112, v2
	v_mov_b32_e32 v113, v2
	v_mov_b32_e32 v122, v2
	v_mov_b32_e32 v123, v2
	v_mov_b32_e32 v124, v2
	v_mov_b32_e32 v125, v2
	v_mov_b32_e32 v126, v2
	v_mov_b32_e32 v127, v2
	v_mov_b32_e32 v128, v2
	v_mov_b32_e32 v129, v2
	v_readfirstlane_b32 s100, v211
	s_cmp_lt_u32 s100, 0x100
	s_cbranch_scc1 .Lpr_lead1
	s_setprio 1
.Lpr_lead1:
.LBB0_554:
	s_add_u32 s30, s2, 0xfff80080
	s_addc_u32 s31, s3, -1
	s_add_i32 s59, 0, 0x10000
	s_cmp_eq_u32 s58, 28
	s_cselect_b32 s41, s37, s31
	s_cselect_b32 s40, s54, s30
	s_cselect_b32 s31, s9, s57
	s_cselect_b32 s30, s55, s56
	s_add_i32 s62, 0, 0x14000
	v_add_u32_e32 v152, s59, v164
	v_add_u32_e32 v160, s62, v164
	ds_read_b128 v[140:143], v152
	ds_read_b128 v[144:147], v152 offset:1024
	ds_read_b128 v[148:151], v152 offset:2048
	ds_read_b128 v[152:155], v152 offset:3072
	ds_read_b128 v[156:159], v160
	ds_read_b128 v[168:171], v160 offset:1024
	ds_read_b128 v[172:175], v160 offset:2048
	ds_read_b128 v[176:179], v160 offset:3072
	v_lshl_add_u64 v[160:161], s[2:3], 0, v[136:137]
	s_add_i32 m0, s24, 0xc000
	ds_read_b128 v[180:183], v167
	ds_read_b128 v[184:187], v167 offset:1024
	ds_read_b128 v[188:191], v167 offset:2048
	ds_read_b128 v[192:195], v167 offset:3072
	ds_read_b128 v[196:199], v167 offset:4096
	ds_read_b128 v[200:203], v167 offset:5120
	ds_read_b128 v[204:207], v167 offset:6144
	ds_read_b128 v[216:219], v167 offset:7168
	global_load_lds_dwordx4 v[160:161], off
	v_lshl_add_u64 v[160:161], s[2:3], 0, v[138:139]
	s_add_i32 m0, s24, 0xe000
	s_nop 0
	global_load_lds_dwordx4 v[160:161], off
	s_waitcnt vmcnt(8)
	s_waitcnt lgkmcnt(0)
	s_barrier
	s_waitcnt lgkmcnt(0)
	v_mfma_f32_16x16x32_bf16 v[126:129], v[140:143], v[180:183], v[126:129]
	v_mfma_f32_16x16x32_bf16 v[122:125], v[148:151], v[180:183], v[122:125]
	v_mfma_f32_16x16x32_bf16 v[110:113], v[140:143], v[188:191], v[110:113]
	v_mfma_f32_16x16x32_bf16 v[106:109], v[148:151], v[188:191], v[106:109]
	v_mfma_f32_16x16x32_bf16 v[94:97], v[140:143], v[196:199], v[94:97]
	v_mfma_f32_16x16x32_bf16 v[90:93], v[148:151], v[196:199], v[90:93]
	v_mfma_f32_16x16x32_bf16 v[78:81], v[140:143], v[204:207], v[78:81]
	v_mfma_f32_16x16x32_bf16 v[74:77], v[148:151], v[204:207], v[74:77]
	v_mfma_f32_16x16x32_bf16 v[126:129], v[144:147], v[184:187], v[126:129]
	v_mfma_f32_16x16x32_bf16 v[122:125], v[152:155], v[184:187], v[122:125]
	v_mfma_f32_16x16x32_bf16 v[110:113], v[144:147], v[192:195], v[110:113]
	v_mfma_f32_16x16x32_bf16 v[106:109], v[152:155], v[192:195], v[106:109]
	v_mfma_f32_16x16x32_bf16 v[94:97], v[144:147], v[200:203], v[94:97]
	v_mfma_f32_16x16x32_bf16 v[90:93], v[152:155], v[200:203], v[90:93]
	v_mfma_f32_16x16x32_bf16 v[78:81], v[144:147], v[216:219], v[78:81]
	v_mfma_f32_16x16x32_bf16 v[74:77], v[152:155], v[216:219], v[74:77]
	v_mfma_f32_16x16x32_bf16 v[118:121], v[156:159], v[180:183], v[118:121]
	v_mfma_f32_16x16x32_bf16 v[114:117], v[172:175], v[180:183], v[114:117]
	v_mfma_f32_16x16x32_bf16 v[102:105], v[156:159], v[188:191], v[102:105]
	v_mfma_f32_16x16x32_bf16 v[98:101], v[172:175], v[188:191], v[98:101]
	v_mfma_f32_16x16x32_bf16 v[86:89], v[156:159], v[196:199], v[86:89]
	v_mfma_f32_16x16x32_bf16 v[82:85], v[172:175], v[196:199], v[82:85]
	v_mfma_f32_16x16x32_bf16 v[70:73], v[156:159], v[204:207], v[70:73]
	v_mfma_f32_16x16x32_bf16 v[66:69], v[172:175], v[204:207], v[66:69]
	v_mfma_f32_16x16x32_bf16 v[118:121], v[168:171], v[184:187], v[118:121]
	v_mfma_f32_16x16x32_bf16 v[114:117], v[176:179], v[184:187], v[114:117]
	v_mfma_f32_16x16x32_bf16 v[102:105], v[168:171], v[192:195], v[102:105]
	v_mfma_f32_16x16x32_bf16 v[98:101], v[176:179], v[192:195], v[98:101]
	v_mfma_f32_16x16x32_bf16 v[86:89], v[168:171], v[200:203], v[86:89]
	v_mfma_f32_16x16x32_bf16 v[82:85], v[176:179], v[200:203], v[82:85]
	v_mfma_f32_16x16x32_bf16 v[70:73], v[168:171], v[216:219], v[70:73]
	v_mfma_f32_16x16x32_bf16 v[66:69], v[176:179], v[216:219], v[66:69]
	s_barrier
	s_add_i32 s59, s59, s19
	v_lshl_add_u64 v[160:161], s[30:31], 0, v[0:1]
	s_mov_b32 m0, s59
	ds_read_b128 v[180:183], v167 offset:16384
	ds_read_b128 v[184:187], v167 offset:17408
	ds_read_b128 v[188:191], v167 offset:18432
	ds_read_b128 v[192:195], v167 offset:19456
	ds_read_b128 v[196:199], v167 offset:20480
	ds_read_b128 v[200:203], v167 offset:21504
	ds_read_b128 v[204:207], v167 offset:22528
	ds_read_b128 v[216:219], v167 offset:23552
	global_load_lds_dwordx4 v[160:161], off
	s_add_i32 m0, s59, 0x2000
	s_add_u32 s60, s30, 0x80000
	v_lshl_add_u64 v[208:209], s[30:31], 0, v[130:131]
	s_addc_u32 s61, s31, 0
	s_add_i32 s59, s62, s19
	global_load_lds_dwordx4 v[208:209], off
	v_lshl_add_u64 v[220:221], s[60:61], 0, v[0:1]
	s_mov_b32 m0, s59
	v_lshl_add_u64 v[222:223], s[40:41], 0, v[132:133]
	global_load_lds_dwordx4 v[220:221], off
	v_lshl_add_u64 v[220:221], s[60:61], 0, v[130:131]
	s_add_i32 m0, s59, 0x2000
	s_nop 0
	global_load_lds_dwordx4 v[220:221], off
	v_lshl_add_u64 v[220:221], s[40:41], 0, v[134:135]
	s_mov_b32 m0, s24
	s_nop 0
	global_load_lds_dwordx4 v[220:221], off
	s_mov_b32 m0, s46
	s_nop 0
	global_load_lds_dwordx4 v[222:223], off
	s_waitcnt vmcnt(8)
	s_waitcnt lgkmcnt(0)
	s_barrier
	s_waitcnt lgkmcnt(0)
	v_mfma_f32_16x16x32_bf16 v[62:65], v[140:143], v[180:183], v[62:65]
	v_mfma_f32_16x16x32_bf16 v[58:61], v[148:151], v[180:183], v[58:61]
	v_mfma_f32_16x16x32_bf16 v[46:49], v[140:143], v[188:191], v[46:49]
	v_mfma_f32_16x16x32_bf16 v[42:45], v[148:151], v[188:191], v[42:45]
	v_mfma_f32_16x16x32_bf16 v[30:33], v[140:143], v[196:199], v[30:33]
	v_mfma_f32_16x16x32_bf16 v[26:29], v[148:151], v[196:199], v[26:29]
	v_mfma_f32_16x16x32_bf16 v[14:17], v[140:143], v[204:207], v[14:17]
	v_mfma_f32_16x16x32_bf16 v[10:13], v[148:151], v[204:207], v[10:13]
	v_mfma_f32_16x16x32_bf16 v[62:65], v[144:147], v[184:187], v[62:65]
	v_mfma_f32_16x16x32_bf16 v[58:61], v[152:155], v[184:187], v[58:61]
	v_mfma_f32_16x16x32_bf16 v[46:49], v[144:147], v[192:195], v[46:49]
	v_mfma_f32_16x16x32_bf16 v[42:45], v[152:155], v[192:195], v[42:45]
	v_mfma_f32_16x16x32_bf16 v[30:33], v[144:147], v[200:203], v[30:33]
	v_mfma_f32_16x16x32_bf16 v[26:29], v[152:155], v[200:203], v[26:29]
	v_mfma_f32_16x16x32_bf16 v[14:17], v[144:147], v[216:219], v[14:17]
	v_mfma_f32_16x16x32_bf16 v[10:13], v[152:155], v[216:219], v[10:13]
	v_mfma_f32_16x16x32_bf16 v[54:57], v[156:159], v[180:183], v[54:57]
	v_mfma_f32_16x16x32_bf16 v[50:53], v[172:175], v[180:183], v[50:53]
	v_mfma_f32_16x16x32_bf16 v[38:41], v[156:159], v[188:191], v[38:41]
	v_mfma_f32_16x16x32_bf16 v[34:37], v[172:175], v[188:191], v[34:37]
	v_mfma_f32_16x16x32_bf16 v[22:25], v[156:159], v[196:199], v[22:25]
	v_mfma_f32_16x16x32_bf16 v[18:21], v[172:175], v[196:199], v[18:21]
	v_mfma_f32_16x16x32_bf16 v[6:9], v[156:159], v[204:207], v[6:9]
	v_mfma_f32_16x16x32_bf16 v[2:5], v[172:175], v[204:207], v[2:5]
	v_mfma_f32_16x16x32_bf16 v[54:57], v[168:171], v[184:187], v[54:57]
	v_mfma_f32_16x16x32_bf16 v[50:53], v[176:179], v[184:187], v[50:53]
	v_mfma_f32_16x16x32_bf16 v[38:41], v[168:171], v[192:195], v[38:41]
	v_mfma_f32_16x16x32_bf16 v[34:37], v[176:179], v[192:195], v[34:37]
	v_mfma_f32_16x16x32_bf16 v[22:25], v[168:171], v[200:203], v[22:25]
	v_mfma_f32_16x16x32_bf16 v[18:21], v[176:179], v[200:203], v[18:21]
	v_mfma_f32_16x16x32_bf16 v[6:9], v[168:171], v[216:219], v[6:9]
	v_mfma_f32_16x16x32_bf16 v[2:5], v[176:179], v[216:219], v[2:5]
	s_barrier
	s_add_i32 s59, 0, 0x18000
	s_add_i32 s60, 0, 0x1c000
	v_add_u32_e32 v152, s59, v164
	v_add_u32_e32 v176, s60, v164
	ds_read_b128 v[140:143], v152
	ds_read_b128 v[144:147], v152 offset:1024
	ds_read_b128 v[148:151], v152 offset:2048
	ds_read_b128 v[152:155], v152 offset:3072
	ds_read_b128 v[156:159], v176
	ds_read_b128 v[168:171], v176 offset:1024
	ds_read_b128 v[172:175], v176 offset:2048
	ds_read_b128 v[176:179], v176 offset:3072
	s_add_u32 s40, s40, 0x80000
	s_addc_u32 s41, s41, 0
	s_mov_b32 m0, s47
	v_lshl_add_u64 v[240:241], s[40:41], 0, v[134:135]
	ds_read_b128 v[180:183], v167 offset:32768
	ds_read_b128 v[184:187], v167 offset:33792
	ds_read_b128 v[188:191], v167 offset:34816
	ds_read_b128 v[192:195], v167 offset:35840
	ds_read_b128 v[196:199], v167 offset:36864
	ds_read_b128 v[200:203], v167 offset:37888
	ds_read_b128 v[204:207], v167 offset:38912
	ds_read_b128 v[216:219], v167 offset:39936
	global_load_lds_dwordx4 v[240:241], off
	v_lshl_add_u64 v[240:241], s[40:41], 0, v[132:133]
	s_mov_b32 m0, s48
	s_nop 0
	global_load_lds_dwordx4 v[240:241], off
	s_waitcnt vmcnt(8)
	s_waitcnt lgkmcnt(0)
	s_barrier
	s_waitcnt lgkmcnt(0)
	v_mfma_f32_16x16x32_bf16 v[126:129], v[140:143], v[180:183], v[126:129]
	v_mfma_f32_16x16x32_bf16 v[122:125], v[148:151], v[180:183], v[122:125]
	v_mfma_f32_16x16x32_bf16 v[110:113], v[140:143], v[188:191], v[110:113]
	v_mfma_f32_16x16x32_bf16 v[106:109], v[148:151], v[188:191], v[106:109]
	v_mfma_f32_16x16x32_bf16 v[94:97], v[140:143], v[196:199], v[94:97]
	v_mfma_f32_16x16x32_bf16 v[90:93], v[148:151], v[196:199], v[90:93]
	v_mfma_f32_16x16x32_bf16 v[78:81], v[140:143], v[204:207], v[78:81]
	v_mfma_f32_16x16x32_bf16 v[74:77], v[148:151], v[204:207], v[74:77]
	v_mfma_f32_16x16x32_bf16 v[126:129], v[144:147], v[184:187], v[126:129]
	v_mfma_f32_16x16x32_bf16 v[122:125], v[152:155], v[184:187], v[122:125]
	v_mfma_f32_16x16x32_bf16 v[110:113], v[144:147], v[192:195], v[110:113]
	v_mfma_f32_16x16x32_bf16 v[106:109], v[152:155], v[192:195], v[106:109]
	v_mfma_f32_16x16x32_bf16 v[94:97], v[144:147], v[200:203], v[94:97]
	v_mfma_f32_16x16x32_bf16 v[90:93], v[152:155], v[200:203], v[90:93]
	v_mfma_f32_16x16x32_bf16 v[78:81], v[144:147], v[216:219], v[78:81]
	v_mfma_f32_16x16x32_bf16 v[74:77], v[152:155], v[216:219], v[74:77]
	v_mfma_f32_16x16x32_bf16 v[118:121], v[156:159], v[180:183], v[118:121]
	v_mfma_f32_16x16x32_bf16 v[114:117], v[172:175], v[180:183], v[114:117]
	v_mfma_f32_16x16x32_bf16 v[102:105], v[156:159], v[188:191], v[102:105]
	v_mfma_f32_16x16x32_bf16 v[98:101], v[172:175], v[188:191], v[98:101]
	v_mfma_f32_16x16x32_bf16 v[86:89], v[156:159], v[196:199], v[86:89]
	v_mfma_f32_16x16x32_bf16 v[82:85], v[172:175], v[196:199], v[82:85]
	v_mfma_f32_16x16x32_bf16 v[70:73], v[156:159], v[204:207], v[70:73]
	v_mfma_f32_16x16x32_bf16 v[66:69], v[172:175], v[204:207], v[66:69]
	v_mfma_f32_16x16x32_bf16 v[118:121], v[168:171], v[184:187], v[118:121]
	v_mfma_f32_16x16x32_bf16 v[114:117], v[176:179], v[184:187], v[114:117]
	v_mfma_f32_16x16x32_bf16 v[102:105], v[168:171], v[192:195], v[102:105]
	v_mfma_f32_16x16x32_bf16 v[98:101], v[176:179], v[192:195], v[98:101]
	v_mfma_f32_16x16x32_bf16 v[86:89], v[168:171], v[200:203], v[86:89]
	v_mfma_f32_16x16x32_bf16 v[82:85], v[176:179], v[200:203], v[82:85]
	v_mfma_f32_16x16x32_bf16 v[70:73], v[168:171], v[216:219], v[70:73]
	v_mfma_f32_16x16x32_bf16 v[66:69], v[176:179], v[216:219], v[66:69]
	s_barrier
	s_add_i32 s40, s59, s19
	v_lshl_add_u64 v[160:161], v[160:161], 0, s[22:23]
	s_mov_b32 m0, s40
	ds_read_b128 v[180:183], v167 offset:49152
	ds_read_b128 v[184:187], v167 offset:50176
	ds_read_b128 v[188:191], v167 offset:51200
	ds_read_b128 v[192:195], v167 offset:52224
	ds_read_b128 v[196:199], v167 offset:53248
	ds_read_b128 v[200:203], v167 offset:54272
	ds_read_b128 v[204:207], v167 offset:55296
	ds_read_b128 v[216:219], v167 offset:56320
	global_load_lds_dwordx4 v[160:161], off
	s_add_i32 m0, s40, 0x2000
	s_add_u32 s30, s30, 0x80080
	v_lshl_add_u64 v[160:161], v[208:209], 0, s[22:23]
	s_addc_u32 s31, s31, 0
	s_add_i32 s40, s60, s19
	global_load_lds_dwordx4 v[160:161], off
	v_lshl_add_u64 v[160:161], s[30:31], 0, v[0:1]
	s_mov_b32 m0, s40
	s_nop 0
	global_load_lds_dwordx4 v[160:161], off
	v_lshl_add_u64 v[160:161], s[30:31], 0, v[130:131]
	s_add_i32 m0, s40, 0x2000
	s_nop 0
	global_load_lds_dwordx4 v[160:161], off
	v_lshl_add_u64 v[160:161], v[220:221], 0, s[22:23]
	s_mov_b32 m0, s49
	s_nop 0
	global_load_lds_dwordx4 v[160:161], off
	v_lshl_add_u64 v[160:161], v[222:223], 0, s[22:23]
	s_mov_b32 m0, s50
	s_nop 0
	global_load_lds_dwordx4 v[160:161], off
	s_waitcnt vmcnt(8)
	s_waitcnt lgkmcnt(0)
	s_barrier
	s_waitcnt lgkmcnt(0)
	v_mfma_f32_16x16x32_bf16 v[62:65], v[140:143], v[180:183], v[62:65]
	v_mfma_f32_16x16x32_bf16 v[58:61], v[148:151], v[180:183], v[58:61]
	v_mfma_f32_16x16x32_bf16 v[46:49], v[140:143], v[188:191], v[46:49]
	v_mfma_f32_16x16x32_bf16 v[42:45], v[148:151], v[188:191], v[42:45]
	v_mfma_f32_16x16x32_bf16 v[30:33], v[140:143], v[196:199], v[30:33]
	v_mfma_f32_16x16x32_bf16 v[26:29], v[148:151], v[196:199], v[26:29]
	v_mfma_f32_16x16x32_bf16 v[14:17], v[140:143], v[204:207], v[14:17]
	v_mfma_f32_16x16x32_bf16 v[10:13], v[148:151], v[204:207], v[10:13]
	v_mfma_f32_16x16x32_bf16 v[62:65], v[144:147], v[184:187], v[62:65]
	v_mfma_f32_16x16x32_bf16 v[58:61], v[152:155], v[184:187], v[58:61]
	v_mfma_f32_16x16x32_bf16 v[46:49], v[144:147], v[192:195], v[46:49]
	v_mfma_f32_16x16x32_bf16 v[42:45], v[152:155], v[192:195], v[42:45]
	v_mfma_f32_16x16x32_bf16 v[30:33], v[144:147], v[200:203], v[30:33]
	v_mfma_f32_16x16x32_bf16 v[26:29], v[152:155], v[200:203], v[26:29]
	v_mfma_f32_16x16x32_bf16 v[14:17], v[144:147], v[216:219], v[14:17]
	v_mfma_f32_16x16x32_bf16 v[10:13], v[152:155], v[216:219], v[10:13]
	v_mfma_f32_16x16x32_bf16 v[54:57], v[156:159], v[180:183], v[54:57]
	v_mfma_f32_16x16x32_bf16 v[50:53], v[172:175], v[180:183], v[50:53]
	v_mfma_f32_16x16x32_bf16 v[38:41], v[156:159], v[188:191], v[38:41]
	v_mfma_f32_16x16x32_bf16 v[34:37], v[172:175], v[188:191], v[34:37]
	v_mfma_f32_16x16x32_bf16 v[22:25], v[156:159], v[196:199], v[22:25]
	v_mfma_f32_16x16x32_bf16 v[18:21], v[172:175], v[196:199], v[18:21]
	v_mfma_f32_16x16x32_bf16 v[6:9], v[156:159], v[204:207], v[6:9]
	v_mfma_f32_16x16x32_bf16 v[2:5], v[172:175], v[204:207], v[2:5]
	v_mfma_f32_16x16x32_bf16 v[54:57], v[168:171], v[184:187], v[54:57]
	v_mfma_f32_16x16x32_bf16 v[50:53], v[176:179], v[184:187], v[50:53]
	v_mfma_f32_16x16x32_bf16 v[38:41], v[168:171], v[192:195], v[38:41]
	v_mfma_f32_16x16x32_bf16 v[34:37], v[176:179], v[192:195], v[34:37]
	v_mfma_f32_16x16x32_bf16 v[22:25], v[168:171], v[200:203], v[22:25]
	v_mfma_f32_16x16x32_bf16 v[18:21], v[176:179], v[200:203], v[18:21]
	v_mfma_f32_16x16x32_bf16 v[6:9], v[168:171], v[216:219], v[6:9]
	v_mfma_f32_16x16x32_bf16 v[2:5], v[176:179], v[216:219], v[2:5]
	s_barrier
	s_add_i32 s58, s58, 2
	s_add_u32 s2, s2, 0x100
	s_addc_u32 s3, s3, 0
	s_add_u32 s56, s56, 0x100
	s_addc_u32 s57, s57, 0
	s_cmp_gt_u32 s58, 29
	s_cbranch_scc0 .LBB0_554
	s_setprio 0
	s_and_b64 vcc, exec, s[6:7]
	s_cbranch_vccz .LBB0_557
	s_barrier

.LBB0_1492:
	s_ashr_i32 s37, s36, 31
	s_lshl_b64 s[40:41], s[36:37], 20
	v_readlane_b32 s44, v253, 60
	v_readlane_b32 s45, v253, 61
	s_add_u32 s9, s44, s40
	s_addc_u32 s37, s45, s41
	s_ashr_i32 s43, s42, 31
	s_lshl_b64 s[40:41], s[42:43], 7
	s_add_u32 s44, s9, s40
	s_addc_u32 s45, s37, s41
	s_and_b64 s[46:47], s[38:39], exec
	s_cselect_b32 s37, s45, s3
	s_cselect_b32 s43, s44, s2
	s_ashr_i32 s9, s8, 31
	s_lshl_b64 s[46:47], s[8:9], 20
	s_add_u32 s9, s17, s46
	s_addc_u32 s47, s18, s47
	s_add_u32 s46, s9, s40
	s_addc_u32 s47, s47, s41
	s_and_b64 s[40:41], s[38:39], exec
	s_cselect_b32 s9, s47, s31
	s_cselect_b32 s59, s46, s30
	s_add_i32 s60, s56, -2
	s_add_u32 s2, s2, 0x80080
	s_addc_u32 s3, s3, 0
	s_add_u32 s61, s30, 0x100
	s_addc_u32 s62, s31, 0
	s_mov_b32 s30, 0
	v_readfirstlane_b32 s100, v211
	s_cmp_lt_u32 s100, 0x100
	s_cbranch_scc1 .Lpr_lead2
	s_setprio 1
.Lpr_lead2:
.LBB0_1493:
	s_add_i32 s63, s30, 2
	s_add_u32 s31, s2, 0xfff80080
	s_addc_u32 s40, s3, -1
	s_add_i32 s64, 0, 0x10000
	s_cmp_eq_u32 s60, s30
	s_cselect_b32 s41, s37, s40
	s_cselect_b32 s40, s43, s31
	v_add_u32_e32 v0, s64, v185
	s_cselect_b32 s31, s9, s62
	s_cselect_b32 s30, s59, s61
	s_add_i32 s66, 0, 0x14000
	ds_read_b128 v[134:137], v0
	ds_read_b128 v[138:141], v0 offset:1024
	ds_read_b128 v[142:145], v0 offset:2048
	ds_read_b128 v[146:149], v0 offset:3072
	v_add_u32_e32 v0, s66, v185
	ds_read_b128 v[150:153], v0
	ds_read_b128 v[154:157], v0 offset:1024
	ds_read_b128 v[158:161], v0 offset:2048
	ds_read_b128 v[176:179], v0 offset:3072
	v_lshl_add_u64 v[2:3], s[2:3], 0, v[172:173]
	s_add_i32 m0, s48, 0xc000
	ds_read_b128 v[180:183], v187
	ds_read_b128 v[190:193], v187 offset:1024
	ds_read_b128 v[194:197], v187 offset:2048
	ds_read_b128 v[198:201], v187 offset:3072
	ds_read_b128 v[202:205], v187 offset:4096
	ds_read_b128 v[206:209], v187 offset:5120
	ds_read_b128 v[216:219], v187 offset:6144
	ds_read_b128 v[220:223], v187 offset:7168
	global_load_lds_dwordx4 v[2:3], off
	v_lshl_add_u64 v[2:3], s[2:3], 0, v[174:175]
	s_add_i32 m0, s48, 0xe000
	s_nop 0
	global_load_lds_dwordx4 v[2:3], off
	s_waitcnt vmcnt(8)
	s_waitcnt lgkmcnt(0)
	s_barrier
	s_waitcnt lgkmcnt(0)
	v_mfma_f32_16x16x32_bf16 v[128:131], v[134:137], v[180:183], v[128:131]
	v_mfma_f32_16x16x32_bf16 v[124:127], v[142:145], v[180:183], v[124:127]
	v_mfma_f32_16x16x32_bf16 v[120:123], v[134:137], v[194:197], v[120:123]
	v_mfma_f32_16x16x32_bf16 v[116:119], v[142:145], v[194:197], v[116:119]
	v_mfma_f32_16x16x32_bf16 v[112:115], v[134:137], v[202:205], v[112:115]
	v_mfma_f32_16x16x32_bf16 v[108:111], v[142:145], v[202:205], v[108:111]
	v_mfma_f32_16x16x32_bf16 v[104:107], v[134:137], v[216:219], v[104:107]
	v_mfma_f32_16x16x32_bf16 v[100:103], v[142:145], v[216:219], v[100:103]
	v_mfma_f32_16x16x32_bf16 v[128:131], v[138:141], v[190:193], v[128:131]
	v_mfma_f32_16x16x32_bf16 v[124:127], v[146:149], v[190:193], v[124:127]
	v_mfma_f32_16x16x32_bf16 v[120:123], v[138:141], v[198:201], v[120:123]
	v_mfma_f32_16x16x32_bf16 v[116:119], v[146:149], v[198:201], v[116:119]
	v_mfma_f32_16x16x32_bf16 v[112:115], v[138:141], v[206:209], v[112:115]
	v_mfma_f32_16x16x32_bf16 v[108:111], v[146:149], v[206:209], v[108:111]
	v_mfma_f32_16x16x32_bf16 v[104:107], v[138:141], v[220:223], v[104:107]
	v_mfma_f32_16x16x32_bf16 v[100:103], v[146:149], v[220:223], v[100:103]
	v_mfma_f32_16x16x32_bf16 v[96:99], v[150:153], v[180:183], v[96:99]
	v_mfma_f32_16x16x32_bf16 v[92:95], v[158:161], v[180:183], v[92:95]
	v_mfma_f32_16x16x32_bf16 v[88:91], v[150:153], v[194:197], v[88:91]
	v_mfma_f32_16x16x32_bf16 v[84:87], v[158:161], v[194:197], v[84:87]
	v_mfma_f32_16x16x32_bf16 v[80:83], v[150:153], v[202:205], v[80:83]
	v_mfma_f32_16x16x32_bf16 v[76:79], v[158:161], v[202:205], v[76:79]
	v_mfma_f32_16x16x32_bf16 v[72:75], v[150:153], v[216:219], v[72:75]
	v_mfma_f32_16x16x32_bf16 v[68:71], v[158:161], v[216:219], v[68:71]
	v_mfma_f32_16x16x32_bf16 v[96:99], v[154:157], v[190:193], v[96:99]
	v_mfma_f32_16x16x32_bf16 v[92:95], v[176:179], v[190:193], v[92:95]
	v_mfma_f32_16x16x32_bf16 v[88:91], v[154:157], v[198:201], v[88:91]
	v_mfma_f32_16x16x32_bf16 v[84:87], v[176:179], v[198:201], v[84:87]
	v_mfma_f32_16x16x32_bf16 v[80:83], v[154:157], v[206:209], v[80:83]
	v_mfma_f32_16x16x32_bf16 v[76:79], v[176:179], v[206:209], v[76:79]
	v_mfma_f32_16x16x32_bf16 v[72:75], v[154:157], v[220:223], v[72:75]
	v_mfma_f32_16x16x32_bf16 v[68:71], v[176:179], v[220:223], v[68:71]
	s_barrier
	s_add_i32 s64, s64, s19
	v_lshl_add_u64 v[162:163], s[30:31], 0, v[168:169]
	s_mov_b32 m0, s64
	ds_read_b128 v[180:183], v187 offset:16384
	ds_read_b128 v[190:193], v187 offset:17408
	ds_read_b128 v[194:197], v187 offset:18432
	ds_read_b128 v[198:201], v187 offset:19456
	ds_read_b128 v[202:205], v187 offset:20480
	ds_read_b128 v[206:209], v187 offset:21504
	ds_read_b128 v[216:219], v187 offset:22528
	ds_read_b128 v[220:223], v187 offset:23552
	global_load_lds_dwordx4 v[162:163], off
	s_add_i32 m0, s64, 0x2000
	s_add_u32 s64, s30, 0x80000
	v_lshl_add_u64 v[240:241], s[30:31], 0, v[164:165]
	s_addc_u32 s65, s31, 0
	s_add_i32 s66, s66, s19
	global_load_lds_dwordx4 v[240:241], off
	v_lshl_add_u64 v[2:3], s[64:65], 0, v[168:169]
	s_mov_b32 m0, s66
	v_lshl_add_u64 v[242:243], s[40:41], 0, v[170:171]
	global_load_lds_dwordx4 v[2:3], off
	v_lshl_add_u64 v[2:3], s[64:65], 0, v[164:165]
	s_add_i32 m0, s66, 0x2000
	v_lshl_add_u64 v[244:245], s[40:41], 0, v[166:167]
	global_load_lds_dwordx4 v[2:3], off
	s_mov_b32 m0, s48
	s_nop 0
	global_load_lds_dwordx4 v[242:243], off
	s_mov_b32 m0, s49
	s_nop 0
	global_load_lds_dwordx4 v[244:245], off
	s_waitcnt vmcnt(8)
	s_waitcnt lgkmcnt(0)
	s_barrier
	s_waitcnt lgkmcnt(0)
	v_mfma_f32_16x16x32_bf16 v[64:67], v[134:137], v[180:183], v[64:67]
	v_mfma_f32_16x16x32_bf16 v[60:63], v[142:145], v[180:183], v[60:63]
	v_mfma_f32_16x16x32_bf16 v[56:59], v[134:137], v[194:197], v[56:59]
	v_mfma_f32_16x16x32_bf16 v[52:55], v[142:145], v[194:197], v[52:55]
	v_mfma_f32_16x16x32_bf16 v[48:51], v[134:137], v[202:205], v[48:51]
	v_mfma_f32_16x16x32_bf16 v[44:47], v[142:145], v[202:205], v[44:47]
	v_mfma_f32_16x16x32_bf16 v[40:43], v[134:137], v[216:219], v[40:43]
	v_mfma_f32_16x16x32_bf16 v[36:39], v[142:145], v[216:219], v[36:39]
	v_mfma_f32_16x16x32_bf16 v[64:67], v[138:141], v[190:193], v[64:67]
	v_mfma_f32_16x16x32_bf16 v[60:63], v[146:149], v[190:193], v[60:63]
	v_mfma_f32_16x16x32_bf16 v[56:59], v[138:141], v[198:201], v[56:59]
	v_mfma_f32_16x16x32_bf16 v[52:55], v[146:149], v[198:201], v[52:55]
	v_mfma_f32_16x16x32_bf16 v[48:51], v[138:141], v[206:209], v[48:51]
	v_mfma_f32_16x16x32_bf16 v[44:47], v[146:149], v[206:209], v[44:47]
	v_mfma_f32_16x16x32_bf16 v[40:43], v[138:141], v[220:223], v[40:43]
	v_mfma_f32_16x16x32_bf16 v[36:39], v[146:149], v[220:223], v[36:39]
	v_mfma_f32_16x16x32_bf16 v[32:35], v[150:153], v[180:183], v[32:35]
	v_mfma_f32_16x16x32_bf16 v[28:31], v[158:161], v[180:183], v[28:31]
	v_mfma_f32_16x16x32_bf16 v[24:27], v[150:153], v[194:197], v[24:27]
	v_mfma_f32_16x16x32_bf16 v[20:23], v[158:161], v[194:197], v[20:23]
	v_mfma_f32_16x16x32_bf16 v[16:19], v[150:153], v[202:205], v[16:19]
	v_mfma_f32_16x16x32_bf16 v[12:15], v[158:161], v[202:205], v[12:15]
	v_mfma_f32_16x16x32_bf16 v[8:11], v[150:153], v[216:219], v[8:11]
	v_mfma_f32_16x16x32_bf16 v[2:5], v[158:161], v[216:219], v[4:7]
	v_mfma_f32_16x16x32_bf16 v[32:35], v[154:157], v[190:193], v[32:35]
	v_mfma_f32_16x16x32_bf16 v[28:31], v[176:179], v[190:193], v[28:31]
	v_mfma_f32_16x16x32_bf16 v[24:27], v[154:157], v[198:201], v[24:27]
	v_mfma_f32_16x16x32_bf16 v[20:23], v[176:179], v[198:201], v[20:23]
	v_mfma_f32_16x16x32_bf16 v[16:19], v[154:157], v[206:209], v[16:19]
	v_mfma_f32_16x16x32_bf16 v[12:15], v[176:179], v[206:209], v[12:15]
	v_mfma_f32_16x16x32_bf16 v[8:11], v[154:157], v[220:223], v[8:11]
	v_mfma_f32_16x16x32_bf16 v[2:5], v[176:179], v[220:223], v[2:5]
	s_barrier
	s_add_i32 s64, 0, 0x18000
	v_add_u32_e32 v0, s64, v185
	s_add_i32 s65, 0, 0x1c000
	ds_read_b128 v[134:137], v0
	ds_read_b128 v[138:141], v0 offset:1024
	ds_read_b128 v[142:145], v0 offset:2048
	ds_read_b128 v[146:149], v0 offset:3072
	v_add_u32_e32 v0, s65, v185
	ds_read_b128 v[150:153], v0
	ds_read_b128 v[154:157], v0 offset:1024
	ds_read_b128 v[158:161], v0 offset:2048
	ds_read_b128 v[176:179], v0 offset:3072
	s_add_u32 s40, s40, 0x80000
	s_addc_u32 s41, s41, 0
	s_mov_b32 m0, s50
	v_lshl_add_u64 v[6:7], s[40:41], 0, v[170:171]
	ds_read_b128 v[180:183], v187 offset:32768
	ds_read_b128 v[190:193], v187 offset:33792
	ds_read_b128 v[194:197], v187 offset:34816
	ds_read_b128 v[198:201], v187 offset:35840
	ds_read_b128 v[202:205], v187 offset:36864
	ds_read_b128 v[206:209], v187 offset:37888
	ds_read_b128 v[216:219], v187 offset:38912
	ds_read_b128 v[220:223], v187 offset:39936
	global_load_lds_dwordx4 v[6:7], off
	v_lshl_add_u64 v[6:7], s[40:41], 0, v[166:167]
	s_mov_b32 m0, s51
	s_nop 0
	global_load_lds_dwordx4 v[6:7], off
	s_waitcnt vmcnt(8)
	s_waitcnt lgkmcnt(0)
	s_barrier
	s_waitcnt lgkmcnt(0)
	v_mfma_f32_16x16x32_bf16 v[128:131], v[134:137], v[180:183], v[128:131]
	v_mfma_f32_16x16x32_bf16 v[124:127], v[142:145], v[180:183], v[124:127]
	v_mfma_f32_16x16x32_bf16 v[120:123], v[134:137], v[194:197], v[120:123]
	v_mfma_f32_16x16x32_bf16 v[116:119], v[142:145], v[194:197], v[116:119]
	v_mfma_f32_16x16x32_bf16 v[112:115], v[134:137], v[202:205], v[112:115]
	v_mfma_f32_16x16x32_bf16 v[108:111], v[142:145], v[202:205], v[108:111]
	v_mfma_f32_16x16x32_bf16 v[104:107], v[134:137], v[216:219], v[104:107]
	v_mfma_f32_16x16x32_bf16 v[100:103], v[142:145], v[216:219], v[100:103]
	v_mfma_f32_16x16x32_bf16 v[128:131], v[138:141], v[190:193], v[128:131]
	v_mfma_f32_16x16x32_bf16 v[124:127], v[146:149], v[190:193], v[124:127]
	v_mfma_f32_16x16x32_bf16 v[120:123], v[138:141], v[198:201], v[120:123]
	v_mfma_f32_16x16x32_bf16 v[116:119], v[146:149], v[198:201], v[116:119]
	v_mfma_f32_16x16x32_bf16 v[112:115], v[138:141], v[206:209], v[112:115]
	v_mfma_f32_16x16x32_bf16 v[108:111], v[146:149], v[206:209], v[108:111]
	v_mfma_f32_16x16x32_bf16 v[104:107], v[138:141], v[220:223], v[104:107]
	v_mfma_f32_16x16x32_bf16 v[100:103], v[146:149], v[220:223], v[100:103]
	v_mfma_f32_16x16x32_bf16 v[96:99], v[150:153], v[180:183], v[96:99]
	v_mfma_f32_16x16x32_bf16 v[92:95], v[158:161], v[180:183], v[92:95]
	v_mfma_f32_16x16x32_bf16 v[88:91], v[150:153], v[194:197], v[88:91]
	v_mfma_f32_16x16x32_bf16 v[84:87], v[158:161], v[194:197], v[84:87]
	v_mfma_f32_16x16x32_bf16 v[80:83], v[150:153], v[202:205], v[80:83]
	v_mfma_f32_16x16x32_bf16 v[76:79], v[158:161], v[202:205], v[76:79]
	v_mfma_f32_16x16x32_bf16 v[72:75], v[150:153], v[216:219], v[72:75]
	v_mfma_f32_16x16x32_bf16 v[68:71], v[158:161], v[216:219], v[68:71]
	v_mfma_f32_16x16x32_bf16 v[96:99], v[154:157], v[190:193], v[96:99]
	v_mfma_f32_16x16x32_bf16 v[92:95], v[176:179], v[190:193], v[92:95]
	v_mfma_f32_16x16x32_bf16 v[88:91], v[154:157], v[198:201], v[88:91]
	v_mfma_f32_16x16x32_bf16 v[84:87], v[176:179], v[198:201], v[84:87]
	v_mfma_f32_16x16x32_bf16 v[80:83], v[154:157], v[206:209], v[80:83]
	v_mfma_f32_16x16x32_bf16 v[76:79], v[176:179], v[206:209], v[76:79]
	v_mfma_f32_16x16x32_bf16 v[72:75], v[154:157], v[220:223], v[72:75]
	v_mfma_f32_16x16x32_bf16 v[68:71], v[176:179], v[220:223], v[68:71]
	s_barrier
	s_add_i32 s40, s64, s19
	v_lshl_add_u64 v[6:7], v[162:163], 0, s[22:23]
	s_mov_b32 m0, s40
	ds_read_b128 v[180:183], v187 offset:49152
	ds_read_b128 v[190:193], v187 offset:50176
	ds_read_b128 v[194:197], v187 offset:51200
	ds_read_b128 v[198:201], v187 offset:52224
	ds_read_b128 v[202:205], v187 offset:53248
	ds_read_b128 v[206:209], v187 offset:54272
	ds_read_b128 v[216:219], v187 offset:55296
	ds_read_b128 v[220:223], v187 offset:56320
	global_load_lds_dwordx4 v[6:7], off
	s_add_i32 m0, s40, 0x2000
	s_add_u32 s30, s30, 0x80080
	v_lshl_add_u64 v[6:7], v[240:241], 0, s[22:23]
	s_addc_u32 s31, s31, 0
	s_add_i32 s40, s65, s19
	global_load_lds_dwordx4 v[6:7], off
	v_lshl_add_u64 v[6:7], s[30:31], 0, v[168:169]
	s_mov_b32 m0, s40
	s_nop 0
	global_load_lds_dwordx4 v[6:7], off
	v_lshl_add_u64 v[6:7], s[30:31], 0, v[164:165]
	s_add_i32 m0, s40, 0x2000
	s_nop 0
	global_load_lds_dwordx4 v[6:7], off
	v_lshl_add_u64 v[6:7], v[242:243], 0, s[22:23]
	s_mov_b32 m0, s52
	s_nop 0
	global_load_lds_dwordx4 v[6:7], off
	v_lshl_add_u64 v[6:7], v[244:245], 0, s[22:23]
	s_mov_b32 m0, s53
	s_nop 0
	global_load_lds_dwordx4 v[6:7], off
	s_waitcnt vmcnt(8)
	s_waitcnt lgkmcnt(0)
	s_barrier
	s_waitcnt lgkmcnt(0)
	v_mfma_f32_16x16x32_bf16 v[64:67], v[134:137], v[180:183], v[64:67]
	v_mfma_f32_16x16x32_bf16 v[60:63], v[142:145], v[180:183], v[60:63]
	v_mfma_f32_16x16x32_bf16 v[56:59], v[134:137], v[194:197], v[56:59]
	v_mfma_f32_16x16x32_bf16 v[52:55], v[142:145], v[194:197], v[52:55]
	v_mfma_f32_16x16x32_bf16 v[48:51], v[134:137], v[202:205], v[48:51]
	v_mfma_f32_16x16x32_bf16 v[44:47], v[142:145], v[202:205], v[44:47]
	v_mfma_f32_16x16x32_bf16 v[40:43], v[134:137], v[216:219], v[40:43]
	v_mfma_f32_16x16x32_bf16 v[36:39], v[142:145], v[216:219], v[36:39]
	v_mfma_f32_16x16x32_bf16 v[64:67], v[138:141], v[190:193], v[64:67]
	v_mfma_f32_16x16x32_bf16 v[60:63], v[146:149], v[190:193], v[60:63]
	v_mfma_f32_16x16x32_bf16 v[56:59], v[138:141], v[198:201], v[56:59]
	v_mfma_f32_16x16x32_bf16 v[52:55], v[146:149], v[198:201], v[52:55]
	v_mfma_f32_16x16x32_bf16 v[48:51], v[138:141], v[206:209], v[48:51]
	v_mfma_f32_16x16x32_bf16 v[44:47], v[146:149], v[206:209], v[44:47]
	v_mfma_f32_16x16x32_bf16 v[40:43], v[138:141], v[220:223], v[40:43]
	v_mfma_f32_16x16x32_bf16 v[36:39], v[146:149], v[220:223], v[36:39]
	v_mfma_f32_16x16x32_bf16 v[32:35], v[150:153], v[180:183], v[32:35]
	v_mfma_f32_16x16x32_bf16 v[28:31], v[158:161], v[180:183], v[28:31]
	v_mfma_f32_16x16x32_bf16 v[24:27], v[150:153], v[194:197], v[24:27]
	v_mfma_f32_16x16x32_bf16 v[20:23], v[158:161], v[194:197], v[20:23]
	v_mfma_f32_16x16x32_bf16 v[16:19], v[150:153], v[202:205], v[16:19]
	v_mfma_f32_16x16x32_bf16 v[12:15], v[158:161], v[202:205], v[12:15]
	v_mfma_f32_16x16x32_bf16 v[6:9], v[150:153], v[216:219], v[8:11]
	v_mfma_f32_16x16x32_bf16 v[2:5], v[158:161], v[216:219], v[2:5]
	v_mfma_f32_16x16x32_bf16 v[32:35], v[154:157], v[190:193], v[32:35]
	v_mfma_f32_16x16x32_bf16 v[28:31], v[176:179], v[190:193], v[28:31]
	v_mfma_f32_16x16x32_bf16 v[24:27], v[154:157], v[198:201], v[24:27]
	v_mfma_f32_16x16x32_bf16 v[20:23], v[176:179], v[198:201], v[20:23]
	v_mfma_f32_16x16x32_bf16 v[16:19], v[154:157], v[206:209], v[16:19]
	v_mfma_f32_16x16x32_bf16 v[12:15], v[176:179], v[206:209], v[12:15]
	v_mfma_f32_16x16x32_bf16 v[8:11], v[154:157], v[220:223], v[6:9]
	v_mfma_f32_16x16x32_bf16 v[4:7], v[176:179], v[220:223], v[2:5]
	s_barrier
	s_add_u32 s2, s2, 0x100
	s_addc_u32 s3, s3, 0
	s_add_u32 s61, s61, 0x100
	s_addc_u32 s62, s62, 0
	s_cmp_ge_i32 s63, s56
	s_mov_b32 s30, s63
	s_cbranch_scc0 .LBB0_1493
	s_setprio 0
	s_and_b64 vcc, exec, s[6:7]
	s_cbranch_vccz .LBB0_1496
	s_barrier

.LBB0_1574:
	s_ashr_i32 s43, s42, 31
	s_lshl_b64 s[44:45], s[42:43], 20
	s_add_u32 s44, s34, s44
	s_addc_u32 s45, s35, s45
	s_and_b64 s[46:47], s[40:41], exec
	s_cselect_b32 s43, s45, s49
	s_cselect_b32 s63, s44, s48
	s_ashr_i32 s37, s36, 31
	s_lshl_b64 s[46:47], s[36:37], 20
	s_add_u32 s46, s17, s46
	s_addc_u32 s47, s18, s47
	s_and_b64 s[52:53], s[40:41], exec
	s_cselect_b32 s37, s47, s51
	s_cselect_b32 s64, s46, s50
	s_add_u32 s48, s48, 0x80080
	s_addc_u32 s49, s49, 0
	s_add_u32 s65, s50, 0x100
	v_mov_b32_e32 v2, 0
	s_addc_u32 s66, s51, 0
	s_mov_b32 s67, -2
	s_waitcnt lgkmcnt(0)
	v_mov_b32_e32 v3, v2
	v_mov_b32_e32 v4, v2
	v_mov_b32_e32 v5, v2
	v_mov_b32_e32 v6, v2
	v_mov_b32_e32 v7, v2
	v_mov_b32_e32 v8, v2
	v_mov_b32_e32 v9, v2
	v_mov_b32_e32 v18, v2
	v_mov_b32_e32 v19, v2
	v_mov_b32_e32 v20, v2
	v_mov_b32_e32 v21, v2
	v_mov_b32_e32 v22, v2
	v_mov_b32_e32 v23, v2
	v_mov_b32_e32 v24, v2
	v_mov_b32_e32 v25, v2
	v_mov_b32_e32 v34, v2
	v_mov_b32_e32 v35, v2
	v_mov_b32_e32 v36, v2
	v_mov_b32_e32 v37, v2
	v_mov_b32_e32 v38, v2
	v_mov_b32_e32 v39, v2
	v_mov_b32_e32 v40, v2
	v_mov_b32_e32 v41, v2
	v_mov_b32_e32 v50, v2
	v_mov_b32_e32 v51, v2
	v_mov_b32_e32 v52, v2
	v_mov_b32_e32 v53, v2
	v_mov_b32_e32 v54, v2
	v_mov_b32_e32 v55, v2
	v_mov_b32_e32 v56, v2
	v_mov_b32_e32 v57, v2
	v_mov_b32_e32 v10, v2
	v_mov_b32_e32 v11, v2
	v_mov_b32_e32 v12, v2
	v_mov_b32_e32 v13, v2
	v_mov_b32_e32 v14, v2
	v_mov_b32_e32 v15, v2
	v_mov_b32_e32 v16, v2
	v_mov_b32_e32 v17, v2
	v_mov_b32_e32 v26, v2
	v_mov_b32_e32 v27, v2
	v_mov_b32_e32 v28, v2
	v_mov_b32_e32 v29, v2
	v_mov_b32_e32 v30, v2
	v_mov_b32_e32 v31, v2
	v_mov_b32_e32 v32, v2
	v_mov_b32_e32 v33, v2
	v_mov_b32_e32 v42, v2
	v_mov_b32_e32 v43, v2
	v_mov_b32_e32 v44, v2
	v_mov_b32_e32 v45, v2
	v_mov_b32_e32 v46, v2
	v_mov_b32_e32 v47, v2
	v_mov_b32_e32 v48, v2
	v_mov_b32_e32 v49, v2
	v_mov_b32_e32 v58, v2
	v_mov_b32_e32 v59, v2
	v_mov_b32_e32 v60, v2
	v_mov_b32_e32 v61, v2
	v_mov_b32_e32 v62, v2
	v_mov_b32_e32 v63, v2
	v_mov_b32_e32 v64, v2
	v_mov_b32_e32 v65, v2
	v_mov_b32_e32 v66, v2
	v_mov_b32_e32 v67, v2
	v_mov_b32_e32 v68, v2
	v_mov_b32_e32 v69, v2
	v_mov_b32_e32 v70, v2
	v_mov_b32_e32 v71, v2
	v_mov_b32_e32 v72, v2
	v_mov_b32_e32 v73, v2
	v_mov_b32_e32 v82, v2
	v_mov_b32_e32 v83, v2
	v_mov_b32_e32 v84, v2
	v_mov_b32_e32 v85, v2
	v_mov_b32_e32 v86, v2
	v_mov_b32_e32 v87, v2
	v_mov_b32_e32 v88, v2
	v_mov_b32_e32 v89, v2
	v_mov_b32_e32 v98, v2
	v_mov_b32_e32 v99, v2
	v_mov_b32_e32 v100, v2
	v_mov_b32_e32 v101, v2
	v_mov_b32_e32 v102, v2
	v_mov_b32_e32 v103, v2
	v_mov_b32_e32 v104, v2
	v_mov_b32_e32 v105, v2
	v_mov_b32_e32 v114, v2
	v_mov_b32_e32 v115, v2
	v_mov_b32_e32 v116, v2
	v_mov_b32_e32 v117, v2
	v_mov_b32_e32 v118, v2
	v_mov_b32_e32 v119, v2
	v_mov_b32_e32 v120, v2
	v_mov_b32_e32 v121, v2
	v_mov_b32_e32 v74, v2
	v_mov_b32_e32 v75, v2
	v_mov_b32_e32 v76, v2
	v_mov_b32_e32 v77, v2
	v_mov_b32_e32 v78, v2
	v_mov_b32_e32 v79, v2
	v_mov_b32_e32 v80, v2
	v_mov_b32_e32 v81, v2
	v_mov_b32_e32 v90, v2
	v_mov_b32_e32 v91, v2
	v_mov_b32_e32 v92, v2
	v_mov_b32_e32 v93, v2
	v_mov_b32_e32 v94, v2
	v_mov_b32_e32 v95, v2
	v_mov_b32_e32 v96, v2
	v_mov_b32_e32 v97, v2
	v_mov_b32_e32 v106, v2
	v_mov_b32_e32 v107, v2
	v_mov_b32_e32 v108, v2
	v_mov_b32_e32 v109, v2
	v_mov_b32_e32 v110, v2
	v_mov_b32_e32 v111, v2
	v_mov_b32_e32 v112, v2
	v_mov_b32_e32 v113, v2
	v_mov_b32_e32 v122, v2
	v_mov_b32_e32 v123, v2
	v_mov_b32_e32 v124, v2
	v_mov_b32_e32 v125, v2
	v_mov_b32_e32 v126, v2
	v_mov_b32_e32 v127, v2
	v_mov_b32_e32 v128, v2
	v_mov_b32_e32 v129, v2
	v_readfirstlane_b32 s100, v211
	s_cmp_lt_u32 s100, 0x100
	s_cbranch_scc1 .Lpr_lead3
	s_setprio 1
.Lpr_lead3:
.LBB0_1575:
	s_add_u32 s50, s48, 0xfff80080
	s_addc_u32 s51, s49, -1
	s_add_i32 s68, 0, 0x10000
	s_cmp_eq_u32 s67, 28
	s_cselect_b32 s53, s43, s51
	s_cselect_b32 s52, s63, s50
	s_cselect_b32 s51, s37, s66
	s_cselect_b32 s50, s64, s65
	s_add_i32 s70, 0, 0x14000
	v_add_u32_e32 v142, s68, v165
	v_add_u32_e32 v172, s70, v165
	ds_read_b128 v[130:133], v142
	ds_read_b128 v[134:137], v142 offset:1024
	ds_read_b128 v[138:141], v142 offset:2048
	ds_read_b128 v[142:145], v142 offset:3072
	ds_read_b128 v[156:159], v172
	ds_read_b128 v[160:163], v172 offset:1024
	ds_read_b128 v[168:171], v172 offset:2048
	ds_read_b128 v[172:175], v172 offset:3072
	v_lshl_add_u64 v[208:209], s[48:49], 0, v[152:153]
	s_add_i32 m0, s54, 0xc000
	ds_read_b128 v[176:179], v167
	ds_read_b128 v[180:183], v167 offset:1024
	ds_read_b128 v[184:187], v167 offset:2048
	ds_read_b128 v[188:191], v167 offset:3072
	ds_read_b128 v[192:195], v167 offset:4096
	ds_read_b128 v[196:199], v167 offset:5120
	ds_read_b128 v[200:203], v167 offset:6144
	ds_read_b128 v[204:207], v167 offset:7168
	global_load_lds_dwordx4 v[208:209], off
	v_lshl_add_u64 v[208:209], s[48:49], 0, v[154:155]
	s_add_i32 m0, s54, 0xe000
	s_nop 0
	global_load_lds_dwordx4 v[208:209], off
	s_waitcnt vmcnt(8)
	s_waitcnt lgkmcnt(0)
	s_barrier
	s_waitcnt lgkmcnt(0)
	v_mfma_f32_16x16x32_bf16 v[126:129], v[130:133], v[176:179], v[126:129]
	v_mfma_f32_16x16x32_bf16 v[122:125], v[138:141], v[176:179], v[122:125]
	v_mfma_f32_16x16x32_bf16 v[110:113], v[130:133], v[184:187], v[110:113]
	v_mfma_f32_16x16x32_bf16 v[106:109], v[138:141], v[184:187], v[106:109]
	v_mfma_f32_16x16x32_bf16 v[94:97], v[130:133], v[192:195], v[94:97]
	v_mfma_f32_16x16x32_bf16 v[90:93], v[138:141], v[192:195], v[90:93]
	v_mfma_f32_16x16x32_bf16 v[78:81], v[130:133], v[200:203], v[78:81]
	v_mfma_f32_16x16x32_bf16 v[74:77], v[138:141], v[200:203], v[74:77]
	v_mfma_f32_16x16x32_bf16 v[126:129], v[134:137], v[180:183], v[126:129]
	v_mfma_f32_16x16x32_bf16 v[122:125], v[142:145], v[180:183], v[122:125]
	v_mfma_f32_16x16x32_bf16 v[110:113], v[134:137], v[188:191], v[110:113]
	v_mfma_f32_16x16x32_bf16 v[106:109], v[142:145], v[188:191], v[106:109]
	v_mfma_f32_16x16x32_bf16 v[94:97], v[134:137], v[196:199], v[94:97]
	v_mfma_f32_16x16x32_bf16 v[90:93], v[142:145], v[196:199], v[90:93]
	v_mfma_f32_16x16x32_bf16 v[78:81], v[134:137], v[204:207], v[78:81]
	v_mfma_f32_16x16x32_bf16 v[74:77], v[142:145], v[204:207], v[74:77]
	v_mfma_f32_16x16x32_bf16 v[118:121], v[156:159], v[176:179], v[118:121]
	v_mfma_f32_16x16x32_bf16 v[114:117], v[168:171], v[176:179], v[114:117]
	v_mfma_f32_16x16x32_bf16 v[102:105], v[156:159], v[184:187], v[102:105]
	v_mfma_f32_16x16x32_bf16 v[98:101], v[168:171], v[184:187], v[98:101]
	v_mfma_f32_16x16x32_bf16 v[86:89], v[156:159], v[192:195], v[86:89]
	v_mfma_f32_16x16x32_bf16 v[82:85], v[168:171], v[192:195], v[82:85]
	v_mfma_f32_16x16x32_bf16 v[70:73], v[156:159], v[200:203], v[70:73]
	v_mfma_f32_16x16x32_bf16 v[66:69], v[168:171], v[200:203], v[66:69]
	v_mfma_f32_16x16x32_bf16 v[118:121], v[160:163], v[180:183], v[118:121]
	v_mfma_f32_16x16x32_bf16 v[114:117], v[172:175], v[180:183], v[114:117]
	v_mfma_f32_16x16x32_bf16 v[102:105], v[160:163], v[188:191], v[102:105]
	v_mfma_f32_16x16x32_bf16 v[98:101], v[172:175], v[188:191], v[98:101]
	v_mfma_f32_16x16x32_bf16 v[86:89], v[160:163], v[196:199], v[86:89]
	v_mfma_f32_16x16x32_bf16 v[82:85], v[172:175], v[196:199], v[82:85]
	v_mfma_f32_16x16x32_bf16 v[70:73], v[160:163], v[204:207], v[70:73]
	v_mfma_f32_16x16x32_bf16 v[66:69], v[172:175], v[204:207], v[66:69]
	s_barrier
	s_add_i32 s68, s68, s19
	v_lshl_add_u64 v[208:209], s[50:51], 0, v[0:1]
	s_mov_b32 m0, s68
	ds_read_b128 v[176:179], v167 offset:16384
	ds_read_b128 v[180:183], v167 offset:17408
	ds_read_b128 v[184:187], v167 offset:18432
	ds_read_b128 v[188:191], v167 offset:19456
	ds_read_b128 v[192:195], v167 offset:20480
	ds_read_b128 v[196:199], v167 offset:21504
	ds_read_b128 v[200:203], v167 offset:22528
	ds_read_b128 v[204:207], v167 offset:23552
	global_load_lds_dwordx4 v[208:209], off
	s_add_i32 m0, s68, 0x2000
	s_add_u32 s68, s50, 0x80000
	v_lshl_add_u64 v[216:217], s[50:51], 0, v[146:147]
	s_addc_u32 s69, s51, 0
	s_add_i32 s70, s70, s19
	global_load_lds_dwordx4 v[216:217], off
	v_lshl_add_u64 v[218:219], s[68:69], 0, v[0:1]
	s_mov_b32 m0, s70
	v_lshl_add_u64 v[220:221], s[52:53], 0, v[148:149]
	global_load_lds_dwordx4 v[218:219], off
	v_lshl_add_u64 v[218:219], s[68:69], 0, v[146:147]
	s_add_i32 m0, s70, 0x2000
	s_nop 0
	global_load_lds_dwordx4 v[218:219], off
	v_lshl_add_u64 v[218:219], s[52:53], 0, v[150:151]
	s_mov_b32 m0, s54
	s_nop 0
	global_load_lds_dwordx4 v[218:219], off
	s_mov_b32 m0, s55
	s_nop 0
	global_load_lds_dwordx4 v[220:221], off
	s_waitcnt vmcnt(8)
	s_waitcnt lgkmcnt(0)
	s_barrier
	s_waitcnt lgkmcnt(0)
	v_mfma_f32_16x16x32_bf16 v[62:65], v[130:133], v[176:179], v[62:65]
	v_mfma_f32_16x16x32_bf16 v[58:61], v[138:141], v[176:179], v[58:61]
	v_mfma_f32_16x16x32_bf16 v[46:49], v[130:133], v[184:187], v[46:49]
	v_mfma_f32_16x16x32_bf16 v[42:45], v[138:141], v[184:187], v[42:45]
	v_mfma_f32_16x16x32_bf16 v[30:33], v[130:133], v[192:195], v[30:33]
	v_mfma_f32_16x16x32_bf16 v[26:29], v[138:141], v[192:195], v[26:29]
	v_mfma_f32_16x16x32_bf16 v[14:17], v[130:133], v[200:203], v[14:17]
	v_mfma_f32_16x16x32_bf16 v[10:13], v[138:141], v[200:203], v[10:13]
	v_mfma_f32_16x16x32_bf16 v[62:65], v[134:137], v[180:183], v[62:65]
	v_mfma_f32_16x16x32_bf16 v[58:61], v[142:145], v[180:183], v[58:61]
	v_mfma_f32_16x16x32_bf16 v[46:49], v[134:137], v[188:191], v[46:49]
	v_mfma_f32_16x16x32_bf16 v[42:45], v[142:145], v[188:191], v[42:45]
	v_mfma_f32_16x16x32_bf16 v[30:33], v[134:137], v[196:199], v[30:33]
	v_mfma_f32_16x16x32_bf16 v[26:29], v[142:145], v[196:199], v[26:29]
	v_mfma_f32_16x16x32_bf16 v[14:17], v[134:137], v[204:207], v[14:17]
	v_mfma_f32_16x16x32_bf16 v[10:13], v[142:145], v[204:207], v[10:13]
	v_mfma_f32_16x16x32_bf16 v[54:57], v[156:159], v[176:179], v[54:57]
	v_mfma_f32_16x16x32_bf16 v[50:53], v[168:171], v[176:179], v[50:53]
	v_mfma_f32_16x16x32_bf16 v[38:41], v[156:159], v[184:187], v[38:41]
	v_mfma_f32_16x16x32_bf16 v[34:37], v[168:171], v[184:187], v[34:37]
	v_mfma_f32_16x16x32_bf16 v[22:25], v[156:159], v[192:195], v[22:25]
	v_mfma_f32_16x16x32_bf16 v[18:21], v[168:171], v[192:195], v[18:21]
	v_mfma_f32_16x16x32_bf16 v[6:9], v[156:159], v[200:203], v[6:9]
	v_mfma_f32_16x16x32_bf16 v[2:5], v[168:171], v[200:203], v[2:5]
	v_mfma_f32_16x16x32_bf16 v[54:57], v[160:163], v[180:183], v[54:57]
	v_mfma_f32_16x16x32_bf16 v[50:53], v[172:175], v[180:183], v[50:53]
	v_mfma_f32_16x16x32_bf16 v[38:41], v[160:163], v[188:191], v[38:41]
	v_mfma_f32_16x16x32_bf16 v[34:37], v[172:175], v[188:191], v[34:37]
	v_mfma_f32_16x16x32_bf16 v[22:25], v[160:163], v[196:199], v[22:25]
	v_mfma_f32_16x16x32_bf16 v[18:21], v[172:175], v[196:199], v[18:21]
	v_mfma_f32_16x16x32_bf16 v[6:9], v[160:163], v[204:207], v[6:9]
	v_mfma_f32_16x16x32_bf16 v[2:5], v[172:175], v[204:207], v[2:5]
	s_barrier
	s_add_i32 s68, 0, 0x18000
	s_add_i32 s69, 0, 0x1c000
	v_add_u32_e32 v142, s68, v165
	v_add_u32_e32 v172, s69, v165
	ds_read_b128 v[130:133], v142
	ds_read_b128 v[134:137], v142 offset:1024
	ds_read_b128 v[138:141], v142 offset:2048
	ds_read_b128 v[142:145], v142 offset:3072
	ds_read_b128 v[156:159], v172
	ds_read_b128 v[160:163], v172 offset:1024
	ds_read_b128 v[168:171], v172 offset:2048
	ds_read_b128 v[172:175], v172 offset:3072
	s_add_u32 s52, s52, 0x80000
	s_addc_u32 s53, s53, 0
	s_mov_b32 m0, s56
	v_lshl_add_u64 v[222:223], s[52:53], 0, v[150:151]
	ds_read_b128 v[176:179], v167 offset:32768
	ds_read_b128 v[180:183], v167 offset:33792
	ds_read_b128 v[184:187], v167 offset:34816
	ds_read_b128 v[188:191], v167 offset:35840
	ds_read_b128 v[192:195], v167 offset:36864
	ds_read_b128 v[196:199], v167 offset:37888
	ds_read_b128 v[200:203], v167 offset:38912
	ds_read_b128 v[204:207], v167 offset:39936
	global_load_lds_dwordx4 v[222:223], off
	v_lshl_add_u64 v[222:223], s[52:53], 0, v[148:149]
	s_mov_b32 m0, s57
	s_nop 0
	global_load_lds_dwordx4 v[222:223], off
	s_waitcnt vmcnt(8)
	s_waitcnt lgkmcnt(0)
	s_barrier
	s_waitcnt lgkmcnt(0)
	v_mfma_f32_16x16x32_bf16 v[126:129], v[130:133], v[176:179], v[126:129]
	v_mfma_f32_16x16x32_bf16 v[122:125], v[138:141], v[176:179], v[122:125]
	v_mfma_f32_16x16x32_bf16 v[110:113], v[130:133], v[184:187], v[110:113]
	v_mfma_f32_16x16x32_bf16 v[106:109], v[138:141], v[184:187], v[106:109]
	v_mfma_f32_16x16x32_bf16 v[94:97], v[130:133], v[192:195], v[94:97]
	v_mfma_f32_16x16x32_bf16 v[90:93], v[138:141], v[192:195], v[90:93]
	v_mfma_f32_16x16x32_bf16 v[78:81], v[130:133], v[200:203], v[78:81]
	v_mfma_f32_16x16x32_bf16 v[74:77], v[138:141], v[200:203], v[74:77]
	v_mfma_f32_16x16x32_bf16 v[126:129], v[134:137], v[180:183], v[126:129]
	v_mfma_f32_16x16x32_bf16 v[122:125], v[142:145], v[180:183], v[122:125]
	v_mfma_f32_16x16x32_bf16 v[110:113], v[134:137], v[188:191], v[110:113]
	v_mfma_f32_16x16x32_bf16 v[106:109], v[142:145], v[188:191], v[106:109]
	v_mfma_f32_16x16x32_bf16 v[94:97], v[134:137], v[196:199], v[94:97]
	v_mfma_f32_16x16x32_bf16 v[90:93], v[142:145], v[196:199], v[90:93]
	v_mfma_f32_16x16x32_bf16 v[78:81], v[134:137], v[204:207], v[78:81]
	v_mfma_f32_16x16x32_bf16 v[74:77], v[142:145], v[204:207], v[74:77]
	v_mfma_f32_16x16x32_bf16 v[118:121], v[156:159], v[176:179], v[118:121]
	v_mfma_f32_16x16x32_bf16 v[114:117], v[168:171], v[176:179], v[114:117]
	v_mfma_f32_16x16x32_bf16 v[102:105], v[156:159], v[184:187], v[102:105]
	v_mfma_f32_16x16x32_bf16 v[98:101], v[168:171], v[184:187], v[98:101]
	v_mfma_f32_16x16x32_bf16 v[86:89], v[156:159], v[192:195], v[86:89]
	v_mfma_f32_16x16x32_bf16 v[82:85], v[168:171], v[192:195], v[82:85]
	v_mfma_f32_16x16x32_bf16 v[70:73], v[156:159], v[200:203], v[70:73]
	v_mfma_f32_16x16x32_bf16 v[66:69], v[168:171], v[200:203], v[66:69]
	v_mfma_f32_16x16x32_bf16 v[118:121], v[160:163], v[180:183], v[118:121]
	v_mfma_f32_16x16x32_bf16 v[114:117], v[172:175], v[180:183], v[114:117]
	v_mfma_f32_16x16x32_bf16 v[102:105], v[160:163], v[188:191], v[102:105]
	v_mfma_f32_16x16x32_bf16 v[98:101], v[172:175], v[188:191], v[98:101]
	v_mfma_f32_16x16x32_bf16 v[86:89], v[160:163], v[196:199], v[86:89]
	v_mfma_f32_16x16x32_bf16 v[82:85], v[172:175], v[196:199], v[82:85]
	v_mfma_f32_16x16x32_bf16 v[70:73], v[160:163], v[204:207], v[70:73]
	v_mfma_f32_16x16x32_bf16 v[66:69], v[172:175], v[204:207], v[66:69]
	s_barrier
	s_add_i32 s52, s68, s19
	v_lshl_add_u64 v[208:209], v[208:209], 0, s[22:23]
	s_mov_b32 m0, s52
	ds_read_b128 v[176:179], v167 offset:49152
	ds_read_b128 v[180:183], v167 offset:50176
	ds_read_b128 v[184:187], v167 offset:51200
	ds_read_b128 v[188:191], v167 offset:52224
	ds_read_b128 v[192:195], v167 offset:53248
	ds_read_b128 v[196:199], v167 offset:54272
	ds_read_b128 v[200:203], v167 offset:55296
	ds_read_b128 v[204:207], v167 offset:56320
	global_load_lds_dwordx4 v[208:209], off
	s_add_i32 m0, s52, 0x2000
	s_add_u32 s50, s50, 0x80080
	v_lshl_add_u64 v[208:209], v[216:217], 0, s[22:23]
	s_addc_u32 s51, s51, 0
	s_add_i32 s52, s69, s19
	global_load_lds_dwordx4 v[208:209], off
	v_lshl_add_u64 v[208:209], s[50:51], 0, v[0:1]
	s_mov_b32 m0, s52
	s_nop 0
	global_load_lds_dwordx4 v[208:209], off
	v_lshl_add_u64 v[208:209], s[50:51], 0, v[146:147]
	s_add_i32 m0, s52, 0x2000
	s_nop 0
	global_load_lds_dwordx4 v[208:209], off
	v_lshl_add_u64 v[208:209], v[218:219], 0, s[22:23]
	s_mov_b32 m0, s59
	s_nop 0
	global_load_lds_dwordx4 v[208:209], off
	v_lshl_add_u64 v[208:209], v[220:221], 0, s[22:23]
	s_mov_b32 m0, s60
	s_nop 0
	global_load_lds_dwordx4 v[208:209], off
	s_waitcnt vmcnt(8)
	s_waitcnt lgkmcnt(0)
	s_barrier
	s_waitcnt lgkmcnt(0)
	v_mfma_f32_16x16x32_bf16 v[62:65], v[130:133], v[176:179], v[62:65]
	v_mfma_f32_16x16x32_bf16 v[58:61], v[138:141], v[176:179], v[58:61]
	v_mfma_f32_16x16x32_bf16 v[46:49], v[130:133], v[184:187], v[46:49]
	v_mfma_f32_16x16x32_bf16 v[42:45], v[138:141], v[184:187], v[42:45]
	v_mfma_f32_16x16x32_bf16 v[30:33], v[130:133], v[192:195], v[30:33]
	v_mfma_f32_16x16x32_bf16 v[26:29], v[138:141], v[192:195], v[26:29]
	v_mfma_f32_16x16x32_bf16 v[14:17], v[130:133], v[200:203], v[14:17]
	v_mfma_f32_16x16x32_bf16 v[10:13], v[138:141], v[200:203], v[10:13]
	v_mfma_f32_16x16x32_bf16 v[62:65], v[134:137], v[180:183], v[62:65]
	v_mfma_f32_16x16x32_bf16 v[58:61], v[142:145], v[180:183], v[58:61]
	v_mfma_f32_16x16x32_bf16 v[46:49], v[134:137], v[188:191], v[46:49]
	v_mfma_f32_16x16x32_bf16 v[42:45], v[142:145], v[188:191], v[42:45]
	v_mfma_f32_16x16x32_bf16 v[30:33], v[134:137], v[196:199], v[30:33]
	v_mfma_f32_16x16x32_bf16 v[26:29], v[142:145], v[196:199], v[26:29]
	v_mfma_f32_16x16x32_bf16 v[14:17], v[134:137], v[204:207], v[14:17]
	v_mfma_f32_16x16x32_bf16 v[10:13], v[142:145], v[204:207], v[10:13]
	v_mfma_f32_16x16x32_bf16 v[54:57], v[156:159], v[176:179], v[54:57]
	v_mfma_f32_16x16x32_bf16 v[50:53], v[168:171], v[176:179], v[50:53]
	v_mfma_f32_16x16x32_bf16 v[38:41], v[156:159], v[184:187], v[38:41]
	v_mfma_f32_16x16x32_bf16 v[34:37], v[168:171], v[184:187], v[34:37]
	v_mfma_f32_16x16x32_bf16 v[22:25], v[156:159], v[192:195], v[22:25]
	v_mfma_f32_16x16x32_bf16 v[18:21], v[168:171], v[192:195], v[18:21]
	v_mfma_f32_16x16x32_bf16 v[6:9], v[156:159], v[200:203], v[6:9]
	v_mfma_f32_16x16x32_bf16 v[2:5], v[168:171], v[200:203], v[2:5]
	v_mfma_f32_16x16x32_bf16 v[54:57], v[160:163], v[180:183], v[54:57]
	v_mfma_f32_16x16x32_bf16 v[50:53], v[172:175], v[180:183], v[50:53]
	v_mfma_f32_16x16x32_bf16 v[38:41], v[160:163], v[188:191], v[38:41]
	v_mfma_f32_16x16x32_bf16 v[34:37], v[172:175], v[188:191], v[34:37]
	v_mfma_f32_16x16x32_bf16 v[22:25], v[160:163], v[196:199], v[22:25]
	v_mfma_f32_16x16x32_bf16 v[18:21], v[172:175], v[196:199], v[18:21]
	v_mfma_f32_16x16x32_bf16 v[6:9], v[160:163], v[204:207], v[6:9]
	v_mfma_f32_16x16x32_bf16 v[2:5], v[172:175], v[204:207], v[2:5]
	s_barrier
	s_add_i32 s67, s67, 2
	s_add_u32 s48, s48, 0x100
	s_addc_u32 s49, s49, 0
	s_add_u32 s65, s65, 0x100
	s_addc_u32 s66, s66, 0
	s_cmp_gt_u32 s67, 29
	s_cbranch_scc0 .LBB0_1575
	s_setprio 0
	s_and_b64 vcc, exec, s[30:31]
	s_cbranch_vccz .LBB0_1578
	s_barrier

.LBB0_1666:
	s_ashr_i32 s41, s40, 31
	s_lshl_b64 s[42:43], s[40:41], 20
	s_add_u32 s42, s4, s42
	s_addc_u32 s43, s5, s43
	s_and_b64 s[44:45], s[38:39], exec
	s_cselect_b32 s41, s43, s1
	s_cselect_b32 s58, s42, s0
	s_ashr_i32 s37, s36, 31
	s_lshl_b64 s[44:45], s[36:37], 20
	s_add_u32 s44, s17, s44
	s_addc_u32 s45, s18, s45
	s_and_b64 s[48:49], s[38:39], exec
	s_cselect_b32 s37, s45, s47
	s_cselect_b32 s59, s44, s46
	s_add_u32 s0, s0, 0x80080
	s_addc_u32 s1, s1, 0
	s_add_u32 s60, s46, 0x100
	v_mov_b32_e32 v2, 0
	s_addc_u32 s61, s47, 0
	s_mov_b32 s62, -2
	v_mov_b32_e32 v3, v2
	v_mov_b32_e32 v4, v2
	v_mov_b32_e32 v5, v2
	v_mov_b32_e32 v6, v2
	v_mov_b32_e32 v7, v2
	v_mov_b32_e32 v8, v2
	v_mov_b32_e32 v9, v2
	v_mov_b32_e32 v18, v2
	v_mov_b32_e32 v19, v2
	s_waitcnt vmcnt(0)
	v_mov_b32_e32 v20, v2
	v_mov_b32_e32 v21, v2
	v_mov_b32_e32 v22, v2
	v_mov_b32_e32 v23, v2
	v_mov_b32_e32 v24, v2
	v_mov_b32_e32 v25, v2
	v_mov_b32_e32 v34, v2
	v_mov_b32_e32 v35, v2
	v_mov_b32_e32 v36, v2
	v_mov_b32_e32 v37, v2
	v_mov_b32_e32 v38, v2
	v_mov_b32_e32 v39, v2
	v_mov_b32_e32 v40, v2
	v_mov_b32_e32 v41, v2
	v_mov_b32_e32 v50, v2
	v_mov_b32_e32 v51, v2
	v_mov_b32_e32 v52, v2
	v_mov_b32_e32 v53, v2
	v_mov_b32_e32 v54, v2
	v_mov_b32_e32 v55, v2
	v_mov_b32_e32 v56, v2
	v_mov_b32_e32 v57, v2
	v_mov_b32_e32 v10, v2
	v_mov_b32_e32 v11, v2
	v_mov_b32_e32 v12, v2
	v_mov_b32_e32 v13, v2
	v_mov_b32_e32 v14, v2
	v_mov_b32_e32 v15, v2
	v_mov_b32_e32 v16, v2
	v_mov_b32_e32 v17, v2
	v_mov_b32_e32 v26, v2
	v_mov_b32_e32 v27, v2
	v_mov_b32_e32 v28, v2
	v_mov_b32_e32 v29, v2
	v_mov_b32_e32 v30, v2
	v_mov_b32_e32 v31, v2
	v_mov_b32_e32 v32, v2
	v_mov_b32_e32 v33, v2
	v_mov_b32_e32 v42, v2
	v_mov_b32_e32 v43, v2
	v_mov_b32_e32 v44, v2
	v_mov_b32_e32 v45, v2
	v_mov_b32_e32 v46, v2
	v_mov_b32_e32 v47, v2
	v_mov_b32_e32 v48, v2
	v_mov_b32_e32 v49, v2
	v_mov_b32_e32 v58, v2
	v_mov_b32_e32 v59, v2
	v_mov_b32_e32 v60, v2
	v_mov_b32_e32 v61, v2
	v_mov_b32_e32 v62, v2
	v_mov_b32_e32 v63, v2
	v_mov_b32_e32 v64, v2
	v_mov_b32_e32 v65, v2
	v_mov_b32_e32 v66, v2
	v_mov_b32_e32 v67, v2
	v_mov_b32_e32 v68, v2
	v_mov_b32_e32 v69, v2
	v_mov_b32_e32 v70, v2
	v_mov_b32_e32 v71, v2
	v_mov_b32_e32 v72, v2
	v_mov_b32_e32 v73, v2
	v_mov_b32_e32 v82, v2
	v_mov_b32_e32 v83, v2
	v_mov_b32_e32 v84, v2
	v_mov_b32_e32 v85, v2
	v_mov_b32_e32 v86, v2
	v_mov_b32_e32 v87, v2
	v_mov_b32_e32 v88, v2
	v_mov_b32_e32 v89, v2
	v_mov_b32_e32 v98, v2
	v_mov_b32_e32 v99, v2
	v_mov_b32_e32 v100, v2
	v_mov_b32_e32 v101, v2
	v_mov_b32_e32 v102, v2
	v_mov_b32_e32 v103, v2
	v_mov_b32_e32 v104, v2
	v_mov_b32_e32 v105, v2
	v_mov_b32_e32 v114, v2
	v_mov_b32_e32 v115, v2
	v_mov_b32_e32 v116, v2
	v_mov_b32_e32 v117, v2
	v_mov_b32_e32 v118, v2
	v_mov_b32_e32 v119, v2
	v_mov_b32_e32 v120, v2
	v_mov_b32_e32 v121, v2
	v_mov_b32_e32 v74, v2
	v_mov_b32_e32 v75, v2
	v_mov_b32_e32 v76, v2
	v_mov_b32_e32 v77, v2
	v_mov_b32_e32 v78, v2
	v_mov_b32_e32 v79, v2
	v_mov_b32_e32 v80, v2
	v_mov_b32_e32 v81, v2
	v_mov_b32_e32 v90, v2
	v_mov_b32_e32 v91, v2
	v_mov_b32_e32 v92, v2
	v_mov_b32_e32 v93, v2
	v_mov_b32_e32 v94, v2
	v_mov_b32_e32 v95, v2
	v_mov_b32_e32 v96, v2
	v_mov_b32_e32 v97, v2
	v_mov_b32_e32 v106, v2
	v_mov_b32_e32 v107, v2
	v_mov_b32_e32 v108, v2
	v_mov_b32_e32 v109, v2
	v_mov_b32_e32 v110, v2
	v_mov_b32_e32 v111, v2
	v_mov_b32_e32 v112, v2
	v_mov_b32_e32 v113, v2
	v_mov_b32_e32 v122, v2
	v_mov_b32_e32 v123, v2
	v_mov_b32_e32 v124, v2
	v_mov_b32_e32 v125, v2
	v_mov_b32_e32 v126, v2
	v_mov_b32_e32 v127, v2
	v_mov_b32_e32 v128, v2
	v_mov_b32_e32 v129, v2
	v_readfirstlane_b32 s100, v211
	s_cmp_lt_u32 s100, 0x100
	s_cbranch_scc1 .Lpr_lead4
	s_setprio 1
.Lpr_lead4:
.LBB0_1667:
	s_add_u32 s46, s0, 0xfff80080
	s_addc_u32 s47, s1, -1
	s_add_i32 s63, 0, 0x10000
	s_cmp_eq_u32 s62, 28
	s_cselect_b32 s49, s41, s47
	s_cselect_b32 s48, s58, s46
	v_add_u32_e32 v150, s63, v157
	s_cselect_b32 s47, s37, s61
	s_cselect_b32 s46, s59, s60
	s_add_i32 s66, 0, 0x14000
	ds_read_b128 v[130:133], v150
	ds_read_b128 v[134:137], v150 offset:1024
	ds_read_b128 v[160:163], v150 offset:2048
	ds_read_b128 v[168:171], v150 offset:3072
	v_add_u32_e32 v150, s66, v157
	ds_read_b128 v[172:175], v150
	ds_read_b128 v[176:179], v150 offset:1024
	ds_read_b128 v[180:183], v150 offset:2048
	ds_read_b128 v[184:187], v150 offset:3072
	v_lshl_add_u64 v[150:151], s[0:1], 0, v[146:147]
	s_add_i32 m0, s24, 0xc000
	ds_read_b128 v[188:191], v167
	ds_read_b128 v[192:195], v167 offset:1024
	ds_read_b128 v[196:199], v167 offset:2048
	ds_read_b128 v[200:203], v167 offset:3072
	ds_read_b128 v[204:207], v167 offset:4096
	ds_read_b128 v[216:219], v167 offset:5120
	ds_read_b128 v[220:223], v167 offset:6144
	ds_read_b128 v[240:243], v167 offset:7168
	global_load_lds_dwordx4 v[150:151], off
	v_lshl_add_u64 v[150:151], s[0:1], 0, v[148:149]
	s_add_i32 m0, s24, 0xe000
	s_nop 0
	global_load_lds_dwordx4 v[150:151], off
	s_waitcnt vmcnt(8)
	s_waitcnt lgkmcnt(0)
	s_barrier
	s_waitcnt lgkmcnt(0)
	v_mfma_f32_16x16x32_bf16 v[126:129], v[130:133], v[188:191], v[126:129]
	v_mfma_f32_16x16x32_bf16 v[122:125], v[160:163], v[188:191], v[122:125]
	v_mfma_f32_16x16x32_bf16 v[110:113], v[130:133], v[196:199], v[110:113]
	v_mfma_f32_16x16x32_bf16 v[106:109], v[160:163], v[196:199], v[106:109]
	v_mfma_f32_16x16x32_bf16 v[94:97], v[130:133], v[204:207], v[94:97]
	v_mfma_f32_16x16x32_bf16 v[90:93], v[160:163], v[204:207], v[90:93]
	v_mfma_f32_16x16x32_bf16 v[78:81], v[130:133], v[220:223], v[78:81]
	v_mfma_f32_16x16x32_bf16 v[74:77], v[160:163], v[220:223], v[74:77]
	v_mfma_f32_16x16x32_bf16 v[126:129], v[134:137], v[192:195], v[126:129]
	v_mfma_f32_16x16x32_bf16 v[122:125], v[168:171], v[192:195], v[122:125]
	v_mfma_f32_16x16x32_bf16 v[110:113], v[134:137], v[200:203], v[110:113]
	v_mfma_f32_16x16x32_bf16 v[106:109], v[168:171], v[200:203], v[106:109]
	v_mfma_f32_16x16x32_bf16 v[94:97], v[134:137], v[216:219], v[94:97]
	v_mfma_f32_16x16x32_bf16 v[90:93], v[168:171], v[216:219], v[90:93]
	v_mfma_f32_16x16x32_bf16 v[78:81], v[134:137], v[240:243], v[78:81]
	v_mfma_f32_16x16x32_bf16 v[74:77], v[168:171], v[240:243], v[74:77]
	v_mfma_f32_16x16x32_bf16 v[118:121], v[172:175], v[188:191], v[118:121]
	v_mfma_f32_16x16x32_bf16 v[114:117], v[180:183], v[188:191], v[114:117]
	v_mfma_f32_16x16x32_bf16 v[102:105], v[172:175], v[196:199], v[102:105]
	v_mfma_f32_16x16x32_bf16 v[98:101], v[180:183], v[196:199], v[98:101]
	v_mfma_f32_16x16x32_bf16 v[86:89], v[172:175], v[204:207], v[86:89]
	v_mfma_f32_16x16x32_bf16 v[82:85], v[180:183], v[204:207], v[82:85]
	v_mfma_f32_16x16x32_bf16 v[70:73], v[172:175], v[220:223], v[70:73]
	v_mfma_f32_16x16x32_bf16 v[66:69], v[180:183], v[220:223], v[66:69]
	v_mfma_f32_16x16x32_bf16 v[118:121], v[176:179], v[192:195], v[118:121]
	v_mfma_f32_16x16x32_bf16 v[114:117], v[184:187], v[192:195], v[114:117]
	v_mfma_f32_16x16x32_bf16 v[102:105], v[176:179], v[200:203], v[102:105]
	v_mfma_f32_16x16x32_bf16 v[98:101], v[184:187], v[200:203], v[98:101]
	v_mfma_f32_16x16x32_bf16 v[86:89], v[176:179], v[216:219], v[86:89]
	v_mfma_f32_16x16x32_bf16 v[82:85], v[184:187], v[216:219], v[82:85]
	v_mfma_f32_16x16x32_bf16 v[70:73], v[176:179], v[240:243], v[70:73]
	v_mfma_f32_16x16x32_bf16 v[66:69], v[184:187], v[240:243], v[66:69]
	s_barrier
	s_add_i32 s63, s63, s19
	v_lshl_add_u64 v[150:151], s[46:47], 0, v[0:1]
	s_mov_b32 m0, s63
	ds_read_b128 v[188:191], v167 offset:16384
	ds_read_b128 v[192:195], v167 offset:17408
	ds_read_b128 v[196:199], v167 offset:18432
	ds_read_b128 v[200:203], v167 offset:19456
	ds_read_b128 v[204:207], v167 offset:20480
	ds_read_b128 v[216:219], v167 offset:21504
	ds_read_b128 v[220:223], v167 offset:22528
	ds_read_b128 v[240:243], v167 offset:23552
	global_load_lds_dwordx4 v[150:151], off
	s_add_i32 m0, s63, 0x2000
	s_add_u32 s64, s46, 0x80000
	v_lshl_add_u64 v[154:155], s[46:47], 0, v[138:139]
	s_addc_u32 s65, s47, 0
	s_add_i32 s63, s66, s19
	global_load_lds_dwordx4 v[154:155], off
	v_lshl_add_u64 v[164:165], s[64:65], 0, v[0:1]
	s_mov_b32 m0, s63
	v_lshl_add_u64 v[208:209], s[48:49], 0, v[140:141]
	global_load_lds_dwordx4 v[164:165], off
	v_lshl_add_u64 v[164:165], s[64:65], 0, v[138:139]
	s_add_i32 m0, s63, 0x2000
	s_nop 0
	global_load_lds_dwordx4 v[164:165], off
	v_lshl_add_u64 v[164:165], s[48:49], 0, v[142:143]
	s_mov_b32 m0, s24
	s_nop 0
	global_load_lds_dwordx4 v[164:165], off
	s_mov_b32 m0, s50
	s_nop 0
	global_load_lds_dwordx4 v[208:209], off
	s_waitcnt vmcnt(8)
	s_waitcnt lgkmcnt(0)
	s_barrier
	s_waitcnt lgkmcnt(0)
	v_mfma_f32_16x16x32_bf16 v[62:65], v[130:133], v[188:191], v[62:65]
	v_mfma_f32_16x16x32_bf16 v[58:61], v[160:163], v[188:191], v[58:61]
	v_mfma_f32_16x16x32_bf16 v[46:49], v[130:133], v[196:199], v[46:49]
	v_mfma_f32_16x16x32_bf16 v[42:45], v[160:163], v[196:199], v[42:45]
	v_mfma_f32_16x16x32_bf16 v[30:33], v[130:133], v[204:207], v[30:33]
	v_mfma_f32_16x16x32_bf16 v[26:29], v[160:163], v[204:207], v[26:29]
	v_mfma_f32_16x16x32_bf16 v[14:17], v[130:133], v[220:223], v[14:17]
	v_mfma_f32_16x16x32_bf16 v[10:13], v[160:163], v[220:223], v[10:13]
	v_mfma_f32_16x16x32_bf16 v[62:65], v[134:137], v[192:195], v[62:65]
	v_mfma_f32_16x16x32_bf16 v[58:61], v[168:171], v[192:195], v[58:61]
	v_mfma_f32_16x16x32_bf16 v[46:49], v[134:137], v[200:203], v[46:49]
	v_mfma_f32_16x16x32_bf16 v[42:45], v[168:171], v[200:203], v[42:45]
	v_mfma_f32_16x16x32_bf16 v[30:33], v[134:137], v[216:219], v[30:33]
	v_mfma_f32_16x16x32_bf16 v[26:29], v[168:171], v[216:219], v[26:29]
	v_mfma_f32_16x16x32_bf16 v[14:17], v[134:137], v[240:243], v[14:17]
	v_mfma_f32_16x16x32_bf16 v[10:13], v[168:171], v[240:243], v[10:13]
	v_mfma_f32_16x16x32_bf16 v[54:57], v[172:175], v[188:191], v[54:57]
	v_mfma_f32_16x16x32_bf16 v[50:53], v[180:183], v[188:191], v[50:53]
	v_mfma_f32_16x16x32_bf16 v[38:41], v[172:175], v[196:199], v[38:41]
	v_mfma_f32_16x16x32_bf16 v[34:37], v[180:183], v[196:199], v[34:37]
	v_mfma_f32_16x16x32_bf16 v[22:25], v[172:175], v[204:207], v[22:25]
	v_mfma_f32_16x16x32_bf16 v[18:21], v[180:183], v[204:207], v[18:21]
	v_mfma_f32_16x16x32_bf16 v[6:9], v[172:175], v[220:223], v[6:9]
	v_mfma_f32_16x16x32_bf16 v[2:5], v[180:183], v[220:223], v[2:5]
	v_mfma_f32_16x16x32_bf16 v[54:57], v[176:179], v[192:195], v[54:57]
	v_mfma_f32_16x16x32_bf16 v[50:53], v[184:187], v[192:195], v[50:53]
	v_mfma_f32_16x16x32_bf16 v[38:41], v[176:179], v[200:203], v[38:41]
	v_mfma_f32_16x16x32_bf16 v[34:37], v[184:187], v[200:203], v[34:37]
	v_mfma_f32_16x16x32_bf16 v[22:25], v[176:179], v[216:219], v[22:25]
	v_mfma_f32_16x16x32_bf16 v[18:21], v[184:187], v[216:219], v[18:21]
	v_mfma_f32_16x16x32_bf16 v[6:9], v[176:179], v[240:243], v[6:9]
	v_mfma_f32_16x16x32_bf16 v[2:5], v[184:187], v[240:243], v[2:5]
	s_barrier
	s_add_i32 s63, 0, 0x18000
	v_add_u32_e32 v152, s63, v157
	s_add_i32 s64, 0, 0x1c000
	ds_read_b128 v[130:133], v152
	ds_read_b128 v[134:137], v152 offset:1024
	ds_read_b128 v[160:163], v152 offset:2048
	ds_read_b128 v[168:171], v152 offset:3072
	v_add_u32_e32 v152, s64, v157
	ds_read_b128 v[172:175], v152
	ds_read_b128 v[176:179], v152 offset:1024
	ds_read_b128 v[180:183], v152 offset:2048
	ds_read_b128 v[184:187], v152 offset:3072
	s_add_u32 s48, s48, 0x80000
	s_addc_u32 s49, s49, 0
	s_mov_b32 m0, s51
	v_lshl_add_u64 v[244:245], s[48:49], 0, v[142:143]
	ds_read_b128 v[188:191], v167 offset:32768
	ds_read_b128 v[192:195], v167 offset:33792
	ds_read_b128 v[196:199], v167 offset:34816
	ds_read_b128 v[200:203], v167 offset:35840
	ds_read_b128 v[204:207], v167 offset:36864
	ds_read_b128 v[216:219], v167 offset:37888
	ds_read_b128 v[220:223], v167 offset:38912
	ds_read_b128 v[240:243], v167 offset:39936
	global_load_lds_dwordx4 v[244:245], off
	v_lshl_add_u64 v[244:245], s[48:49], 0, v[140:141]
	s_mov_b32 m0, s52
	s_nop 0
	global_load_lds_dwordx4 v[244:245], off
	s_waitcnt vmcnt(8)
	s_waitcnt lgkmcnt(0)
	s_barrier
	s_waitcnt lgkmcnt(0)
	v_mfma_f32_16x16x32_bf16 v[126:129], v[130:133], v[188:191], v[126:129]
	v_mfma_f32_16x16x32_bf16 v[122:125], v[160:163], v[188:191], v[122:125]
	v_mfma_f32_16x16x32_bf16 v[110:113], v[130:133], v[196:199], v[110:113]
	v_mfma_f32_16x16x32_bf16 v[106:109], v[160:163], v[196:199], v[106:109]
	v_mfma_f32_16x16x32_bf16 v[94:97], v[130:133], v[204:207], v[94:97]
	v_mfma_f32_16x16x32_bf16 v[90:93], v[160:163], v[204:207], v[90:93]
	v_mfma_f32_16x16x32_bf16 v[78:81], v[130:133], v[220:223], v[78:81]
	v_mfma_f32_16x16x32_bf16 v[74:77], v[160:163], v[220:223], v[74:77]
	v_mfma_f32_16x16x32_bf16 v[126:129], v[134:137], v[192:195], v[126:129]
	v_mfma_f32_16x16x32_bf16 v[122:125], v[168:171], v[192:195], v[122:125]
	v_mfma_f32_16x16x32_bf16 v[110:113], v[134:137], v[200:203], v[110:113]
	v_mfma_f32_16x16x32_bf16 v[106:109], v[168:171], v[200:203], v[106:109]
	v_mfma_f32_16x16x32_bf16 v[94:97], v[134:137], v[216:219], v[94:97]
	v_mfma_f32_16x16x32_bf16 v[90:93], v[168:171], v[216:219], v[90:93]
	v_mfma_f32_16x16x32_bf16 v[78:81], v[134:137], v[240:243], v[78:81]
	v_mfma_f32_16x16x32_bf16 v[74:77], v[168:171], v[240:243], v[74:77]
	v_mfma_f32_16x16x32_bf16 v[118:121], v[172:175], v[188:191], v[118:121]
	v_mfma_f32_16x16x32_bf16 v[114:117], v[180:183], v[188:191], v[114:117]
	v_mfma_f32_16x16x32_bf16 v[102:105], v[172:175], v[196:199], v[102:105]
	v_mfma_f32_16x16x32_bf16 v[98:101], v[180:183], v[196:199], v[98:101]
	v_mfma_f32_16x16x32_bf16 v[86:89], v[172:175], v[204:207], v[86:89]
	v_mfma_f32_16x16x32_bf16 v[82:85], v[180:183], v[204:207], v[82:85]
	v_mfma_f32_16x16x32_bf16 v[70:73], v[172:175], v[220:223], v[70:73]
	v_mfma_f32_16x16x32_bf16 v[66:69], v[180:183], v[220:223], v[66:69]
	v_mfma_f32_16x16x32_bf16 v[118:121], v[176:179], v[192:195], v[118:121]
	v_mfma_f32_16x16x32_bf16 v[114:117], v[184:187], v[192:195], v[114:117]
	v_mfma_f32_16x16x32_bf16 v[102:105], v[176:179], v[200:203], v[102:105]
	v_mfma_f32_16x16x32_bf16 v[98:101], v[184:187], v[200:203], v[98:101]
	v_mfma_f32_16x16x32_bf16 v[86:89], v[176:179], v[216:219], v[86:89]
	v_mfma_f32_16x16x32_bf16 v[82:85], v[184:187], v[216:219], v[82:85]
	v_mfma_f32_16x16x32_bf16 v[70:73], v[176:179], v[240:243], v[70:73]
	v_mfma_f32_16x16x32_bf16 v[66:69], v[184:187], v[240:243], v[66:69]
	s_barrier
	s_add_i32 s48, s63, s19
	v_lshl_add_u64 v[150:151], v[150:151], 0, s[22:23]
	s_mov_b32 m0, s48
	ds_read_b128 v[188:191], v167 offset:49152
	ds_read_b128 v[192:195], v167 offset:50176
	ds_read_b128 v[196:199], v167 offset:51200
	ds_read_b128 v[200:203], v167 offset:52224
	ds_read_b128 v[204:207], v167 offset:53248
	ds_read_b128 v[216:219], v167 offset:54272
	ds_read_b128 v[220:223], v167 offset:55296
	ds_read_b128 v[240:243], v167 offset:56320
	global_load_lds_dwordx4 v[150:151], off
	s_add_i32 m0, s48, 0x2000
	s_add_u32 s46, s46, 0x80080
	v_lshl_add_u64 v[150:151], v[154:155], 0, s[22:23]
	s_addc_u32 s47, s47, 0
	s_add_i32 s48, s64, s19
	global_load_lds_dwordx4 v[150:151], off
	v_lshl_add_u64 v[150:151], s[46:47], 0, v[0:1]
	s_mov_b32 m0, s48
	s_nop 0
	global_load_lds_dwordx4 v[150:151], off
	v_lshl_add_u64 v[150:151], s[46:47], 0, v[138:139]
	s_add_i32 m0, s48, 0x2000
	s_nop 0
	global_load_lds_dwordx4 v[150:151], off
	v_lshl_add_u64 v[150:151], v[164:165], 0, s[22:23]
	s_mov_b32 m0, s53
	s_nop 0
	global_load_lds_dwordx4 v[150:151], off
	v_lshl_add_u64 v[150:151], v[208:209], 0, s[22:23]
	s_mov_b32 m0, s54
	s_nop 0
	global_load_lds_dwordx4 v[150:151], off
	s_waitcnt vmcnt(8)
	s_waitcnt lgkmcnt(0)
	s_barrier
	s_waitcnt lgkmcnt(0)
	v_mfma_f32_16x16x32_bf16 v[62:65], v[130:133], v[188:191], v[62:65]
	v_mfma_f32_16x16x32_bf16 v[58:61], v[160:163], v[188:191], v[58:61]
	v_mfma_f32_16x16x32_bf16 v[46:49], v[130:133], v[196:199], v[46:49]
	v_mfma_f32_16x16x32_bf16 v[42:45], v[160:163], v[196:199], v[42:45]
	v_mfma_f32_16x16x32_bf16 v[30:33], v[130:133], v[204:207], v[30:33]
	v_mfma_f32_16x16x32_bf16 v[26:29], v[160:163], v[204:207], v[26:29]
	v_mfma_f32_16x16x32_bf16 v[14:17], v[130:133], v[220:223], v[14:17]
	v_mfma_f32_16x16x32_bf16 v[10:13], v[160:163], v[220:223], v[10:13]
	v_mfma_f32_16x16x32_bf16 v[62:65], v[134:137], v[192:195], v[62:65]
	v_mfma_f32_16x16x32_bf16 v[58:61], v[168:171], v[192:195], v[58:61]
	v_mfma_f32_16x16x32_bf16 v[46:49], v[134:137], v[200:203], v[46:49]
	v_mfma_f32_16x16x32_bf16 v[42:45], v[168:171], v[200:203], v[42:45]
	v_mfma_f32_16x16x32_bf16 v[30:33], v[134:137], v[216:219], v[30:33]
	v_mfma_f32_16x16x32_bf16 v[26:29], v[168:171], v[216:219], v[26:29]
	v_mfma_f32_16x16x32_bf16 v[14:17], v[134:137], v[240:243], v[14:17]
	v_mfma_f32_16x16x32_bf16 v[10:13], v[168:171], v[240:243], v[10:13]
	v_mfma_f32_16x16x32_bf16 v[54:57], v[172:175], v[188:191], v[54:57]
	v_mfma_f32_16x16x32_bf16 v[50:53], v[180:183], v[188:191], v[50:53]
	v_mfma_f32_16x16x32_bf16 v[38:41], v[172:175], v[196:199], v[38:41]
	v_mfma_f32_16x16x32_bf16 v[34:37], v[180:183], v[196:199], v[34:37]
	v_mfma_f32_16x16x32_bf16 v[22:25], v[172:175], v[204:207], v[22:25]
	v_mfma_f32_16x16x32_bf16 v[18:21], v[180:183], v[204:207], v[18:21]
	v_mfma_f32_16x16x32_bf16 v[6:9], v[172:175], v[220:223], v[6:9]
	v_mfma_f32_16x16x32_bf16 v[2:5], v[180:183], v[220:223], v[2:5]
	v_mfma_f32_16x16x32_bf16 v[54:57], v[176:179], v[192:195], v[54:57]
	v_mfma_f32_16x16x32_bf16 v[50:53], v[184:187], v[192:195], v[50:53]
	v_mfma_f32_16x16x32_bf16 v[38:41], v[176:179], v[200:203], v[38:41]
	v_mfma_f32_16x16x32_bf16 v[34:37], v[184:187], v[200:203], v[34:37]
	v_mfma_f32_16x16x32_bf16 v[22:25], v[176:179], v[216:219], v[22:25]
	v_mfma_f32_16x16x32_bf16 v[18:21], v[184:187], v[216:219], v[18:21]
	v_mfma_f32_16x16x32_bf16 v[6:9], v[176:179], v[240:243], v[6:9]
	v_mfma_f32_16x16x32_bf16 v[2:5], v[184:187], v[240:243], v[2:5]
	s_barrier
	s_add_i32 s62, s62, 2
	s_add_u32 s0, s0, 0x100
	s_addc_u32 s1, s1, 0
	s_add_u32 s60, s60, 0x100
	s_addc_u32 s61, s61, 0
	s_cmp_gt_u32 s62, 29
	s_cbranch_scc0 .LBB0_1667
	s_setprio 0
	s_and_b64 vcc, exec, s[30:31]
	s_cbranch_vccz .LBB0_1670
	s_barrier

.LBB0_1762:
	s_ashr_i32 s37, s36, 31
	s_lshl_b64 s[42:43], s[36:37], 22
	s_add_u32 s42, s28, s42
	s_addc_u32 s43, s29, s43
	s_and_b64 s[44:45], s[40:41], exec
	s_cselect_b32 s37, s43, s47
	s_cselect_b32 s61, s42, s46
	s_ashr_i32 s31, s30, 31
	s_lshl_b64 s[44:45], s[30:31], 22
	s_add_u32 s44, s17, s44
	s_addc_u32 s45, s18, s45
	s_and_b64 s[50:51], s[40:41], exec
	s_cselect_b32 s31, s45, s49
	s_cselect_b32 s62, s44, s48
	s_add_u32 s46, s46, 0x200080
	s_addc_u32 s47, s47, 0
	s_add_u32 s63, s48, 0x100
	v_mov_b32_e32 v2, 0
	s_addc_u32 s64, s49, 0
	s_mov_b32 s65, -2
	s_waitcnt lgkmcnt(0)
	v_mov_b32_e32 v3, v2
	v_mov_b32_e32 v4, v2
	v_mov_b32_e32 v5, v2
	v_mov_b32_e32 v6, v2
	v_mov_b32_e32 v7, v2
	v_mov_b32_e32 v8, v2
	v_mov_b32_e32 v9, v2
	v_mov_b32_e32 v18, v2
	v_mov_b32_e32 v19, v2
	v_mov_b32_e32 v20, v2
	v_mov_b32_e32 v21, v2
	v_mov_b32_e32 v22, v2
	v_mov_b32_e32 v23, v2
	v_mov_b32_e32 v24, v2
	v_mov_b32_e32 v25, v2
	v_mov_b32_e32 v34, v2
	v_mov_b32_e32 v35, v2
	v_mov_b32_e32 v36, v2
	v_mov_b32_e32 v37, v2
	v_mov_b32_e32 v38, v2
	v_mov_b32_e32 v39, v2
	v_mov_b32_e32 v40, v2
	v_mov_b32_e32 v41, v2
	v_mov_b32_e32 v50, v2
	v_mov_b32_e32 v51, v2
	v_mov_b32_e32 v52, v2
	v_mov_b32_e32 v53, v2
	v_mov_b32_e32 v54, v2
	v_mov_b32_e32 v55, v2
	v_mov_b32_e32 v56, v2
	v_mov_b32_e32 v57, v2
	v_mov_b32_e32 v10, v2
	v_mov_b32_e32 v11, v2
	v_mov_b32_e32 v12, v2
	v_mov_b32_e32 v13, v2
	v_mov_b32_e32 v14, v2
	v_mov_b32_e32 v15, v2
	v_mov_b32_e32 v16, v2
	v_mov_b32_e32 v17, v2
	v_mov_b32_e32 v26, v2
	v_mov_b32_e32 v27, v2
	v_mov_b32_e32 v28, v2
	v_mov_b32_e32 v29, v2
	v_mov_b32_e32 v30, v2
	v_mov_b32_e32 v31, v2
	v_mov_b32_e32 v32, v2
	v_mov_b32_e32 v33, v2
	v_mov_b32_e32 v42, v2
	v_mov_b32_e32 v43, v2
	v_mov_b32_e32 v44, v2
	v_mov_b32_e32 v45, v2
	v_mov_b32_e32 v46, v2
	v_mov_b32_e32 v47, v2
	v_mov_b32_e32 v48, v2
	v_mov_b32_e32 v49, v2
	v_mov_b32_e32 v58, v2
	v_mov_b32_e32 v59, v2
	v_mov_b32_e32 v60, v2
	v_mov_b32_e32 v61, v2
	v_mov_b32_e32 v62, v2
	v_mov_b32_e32 v63, v2
	v_mov_b32_e32 v64, v2
	v_mov_b32_e32 v65, v2
	v_mov_b32_e32 v66, v2
	v_mov_b32_e32 v67, v2
	v_mov_b32_e32 v68, v2
	v_mov_b32_e32 v69, v2
	v_mov_b32_e32 v70, v2
	v_mov_b32_e32 v71, v2
	v_mov_b32_e32 v72, v2
	v_mov_b32_e32 v73, v2
	v_mov_b32_e32 v82, v2
	v_mov_b32_e32 v83, v2
	v_mov_b32_e32 v84, v2
	v_mov_b32_e32 v85, v2
	v_mov_b32_e32 v86, v2
	v_mov_b32_e32 v87, v2
	v_mov_b32_e32 v88, v2
	v_mov_b32_e32 v89, v2
	v_mov_b32_e32 v98, v2
	v_mov_b32_e32 v99, v2
	v_mov_b32_e32 v100, v2
	v_mov_b32_e32 v101, v2
	v_mov_b32_e32 v102, v2
	v_mov_b32_e32 v103, v2
	v_mov_b32_e32 v104, v2
	v_mov_b32_e32 v105, v2
	v_mov_b32_e32 v114, v2
	v_mov_b32_e32 v115, v2
	v_mov_b32_e32 v116, v2
	v_mov_b32_e32 v117, v2
	v_mov_b32_e32 v118, v2
	v_mov_b32_e32 v119, v2
	v_mov_b32_e32 v120, v2
	v_mov_b32_e32 v121, v2
	v_mov_b32_e32 v74, v2
	v_mov_b32_e32 v75, v2
	v_mov_b32_e32 v76, v2
	v_mov_b32_e32 v77, v2
	v_mov_b32_e32 v78, v2
	v_mov_b32_e32 v79, v2
	v_mov_b32_e32 v80, v2
	v_mov_b32_e32 v81, v2
	v_mov_b32_e32 v90, v2
	v_mov_b32_e32 v91, v2
	v_mov_b32_e32 v92, v2
	v_mov_b32_e32 v93, v2
	v_mov_b32_e32 v94, v2
	v_mov_b32_e32 v95, v2
	v_mov_b32_e32 v96, v2
	v_mov_b32_e32 v97, v2
	v_mov_b32_e32 v106, v2
	v_mov_b32_e32 v107, v2
	v_mov_b32_e32 v108, v2
	v_mov_b32_e32 v109, v2
	v_mov_b32_e32 v110, v2
	v_mov_b32_e32 v111, v2
	v_mov_b32_e32 v112, v2
	v_mov_b32_e32 v113, v2
	v_mov_b32_e32 v122, v2
	v_mov_b32_e32 v123, v2
	v_mov_b32_e32 v124, v2
	v_mov_b32_e32 v125, v2
	v_mov_b32_e32 v126, v2
	v_mov_b32_e32 v127, v2
	v_mov_b32_e32 v128, v2
	v_mov_b32_e32 v129, v2
	v_readfirstlane_b32 s100, v211
	s_cmp_lt_u32 s100, 0x100
	s_cbranch_scc1 .Lpr_lead5
	s_setprio 1
.Lpr_lead5:
.LBB0_1763:
	s_add_u32 s48, s46, 0xffe00080
	s_addc_u32 s49, s47, -1
	s_add_i32 s66, 0, 0x10000
	s_cmpk_eq_i32 s65, 0x7c
	s_cselect_b32 s51, s37, s49
	s_cselect_b32 s50, s61, s48
	s_cselect_b32 s49, s31, s64
	s_cselect_b32 s48, s62, s63
	s_add_i32 s68, 0, 0x14000
	v_add_u32_e32 v142, s66, v167
	v_add_u32_e32 v164, s68, v167
	ds_read_b128 v[130:133], v142
	ds_read_b128 v[134:137], v142 offset:1024
	ds_read_b128 v[138:141], v142 offset:2048
	ds_read_b128 v[142:145], v142 offset:3072
	ds_read_b128 v[156:159], v164
	ds_read_b128 v[160:163], v164 offset:1024
	ds_read_b128 v[170:173], v164 offset:2048
	ds_read_b128 v[174:177], v164 offset:3072
	v_lshl_add_u64 v[164:165], s[46:47], 0, v[152:153]
	s_add_i32 m0, s52, 0xc000
	ds_read_b128 v[178:181], v169
	ds_read_b128 v[182:185], v169 offset:1024
	ds_read_b128 v[186:189], v169 offset:2048
	ds_read_b128 v[190:193], v169 offset:3072
	ds_read_b128 v[194:197], v169 offset:4096
	ds_read_b128 v[198:201], v169 offset:5120
	ds_read_b128 v[202:205], v169 offset:6144
	ds_read_b128 v[206:209], v169 offset:7168
	global_load_lds_dwordx4 v[164:165], off
	v_lshl_add_u64 v[164:165], s[46:47], 0, v[154:155]
	s_add_i32 m0, s52, 0xe000
	s_nop 0
	global_load_lds_dwordx4 v[164:165], off
	s_waitcnt vmcnt(8)
	s_waitcnt lgkmcnt(0)
	s_barrier
	s_waitcnt lgkmcnt(0)
	v_mfma_f32_16x16x32_bf16 v[126:129], v[130:133], v[178:181], v[126:129]
	v_mfma_f32_16x16x32_bf16 v[122:125], v[138:141], v[178:181], v[122:125]
	v_mfma_f32_16x16x32_bf16 v[110:113], v[130:133], v[186:189], v[110:113]
	v_mfma_f32_16x16x32_bf16 v[106:109], v[138:141], v[186:189], v[106:109]
	v_mfma_f32_16x16x32_bf16 v[94:97], v[130:133], v[194:197], v[94:97]
	v_mfma_f32_16x16x32_bf16 v[90:93], v[138:141], v[194:197], v[90:93]
	v_mfma_f32_16x16x32_bf16 v[78:81], v[130:133], v[202:205], v[78:81]
	v_mfma_f32_16x16x32_bf16 v[74:77], v[138:141], v[202:205], v[74:77]
	v_mfma_f32_16x16x32_bf16 v[126:129], v[134:137], v[182:185], v[126:129]
	v_mfma_f32_16x16x32_bf16 v[122:125], v[142:145], v[182:185], v[122:125]
	v_mfma_f32_16x16x32_bf16 v[110:113], v[134:137], v[190:193], v[110:113]
	v_mfma_f32_16x16x32_bf16 v[106:109], v[142:145], v[190:193], v[106:109]
	v_mfma_f32_16x16x32_bf16 v[94:97], v[134:137], v[198:201], v[94:97]
	v_mfma_f32_16x16x32_bf16 v[90:93], v[142:145], v[198:201], v[90:93]
	v_mfma_f32_16x16x32_bf16 v[78:81], v[134:137], v[206:209], v[78:81]
	v_mfma_f32_16x16x32_bf16 v[74:77], v[142:145], v[206:209], v[74:77]
	v_mfma_f32_16x16x32_bf16 v[118:121], v[156:159], v[178:181], v[118:121]
	v_mfma_f32_16x16x32_bf16 v[114:117], v[170:173], v[178:181], v[114:117]
	v_mfma_f32_16x16x32_bf16 v[102:105], v[156:159], v[186:189], v[102:105]
	v_mfma_f32_16x16x32_bf16 v[98:101], v[170:173], v[186:189], v[98:101]
	v_mfma_f32_16x16x32_bf16 v[86:89], v[156:159], v[194:197], v[86:89]
	v_mfma_f32_16x16x32_bf16 v[82:85], v[170:173], v[194:197], v[82:85]
	v_mfma_f32_16x16x32_bf16 v[70:73], v[156:159], v[202:205], v[70:73]
	v_mfma_f32_16x16x32_bf16 v[66:69], v[170:173], v[202:205], v[66:69]
	v_mfma_f32_16x16x32_bf16 v[118:121], v[160:163], v[182:185], v[118:121]
	v_mfma_f32_16x16x32_bf16 v[114:117], v[174:177], v[182:185], v[114:117]
	v_mfma_f32_16x16x32_bf16 v[102:105], v[160:163], v[190:193], v[102:105]
	v_mfma_f32_16x16x32_bf16 v[98:101], v[174:177], v[190:193], v[98:101]
	v_mfma_f32_16x16x32_bf16 v[86:89], v[160:163], v[198:201], v[86:89]
	v_mfma_f32_16x16x32_bf16 v[82:85], v[174:177], v[198:201], v[82:85]
	v_mfma_f32_16x16x32_bf16 v[70:73], v[160:163], v[206:209], v[70:73]
	v_mfma_f32_16x16x32_bf16 v[66:69], v[174:177], v[206:209], v[66:69]
	s_barrier
	s_add_i32 s66, s66, s19
	v_lshl_add_u64 v[164:165], s[48:49], 0, v[0:1]
	s_mov_b32 m0, s66
	ds_read_b128 v[178:181], v169 offset:16384
	ds_read_b128 v[182:185], v169 offset:17408
	ds_read_b128 v[186:189], v169 offset:18432
	ds_read_b128 v[190:193], v169 offset:19456
	ds_read_b128 v[194:197], v169 offset:20480
	ds_read_b128 v[198:201], v169 offset:21504
	ds_read_b128 v[202:205], v169 offset:22528
	ds_read_b128 v[206:209], v169 offset:23552
	global_load_lds_dwordx4 v[164:165], off
	s_add_i32 m0, s66, 0x2000
	s_add_u32 s66, s48, 0x200000
	v_lshl_add_u64 v[216:217], s[48:49], 0, v[146:147]
	s_addc_u32 s67, s49, 0
	s_add_i32 s68, s68, s19
	global_load_lds_dwordx4 v[216:217], off
	v_lshl_add_u64 v[218:219], s[66:67], 0, v[0:1]
	s_mov_b32 m0, s68
	v_lshl_add_u64 v[220:221], s[50:51], 0, v[148:149]
	global_load_lds_dwordx4 v[218:219], off
	v_lshl_add_u64 v[218:219], s[66:67], 0, v[146:147]
	s_add_i32 m0, s68, 0x2000
	s_nop 0
	global_load_lds_dwordx4 v[218:219], off
	v_lshl_add_u64 v[218:219], s[50:51], 0, v[150:151]
	s_mov_b32 m0, s52
	s_nop 0
	global_load_lds_dwordx4 v[218:219], off
	s_mov_b32 m0, s53
	s_nop 0
	global_load_lds_dwordx4 v[220:221], off
	s_waitcnt vmcnt(8)
	s_waitcnt lgkmcnt(0)
	s_barrier
	s_waitcnt lgkmcnt(0)
	v_mfma_f32_16x16x32_bf16 v[62:65], v[130:133], v[178:181], v[62:65]
	v_mfma_f32_16x16x32_bf16 v[58:61], v[138:141], v[178:181], v[58:61]
	v_mfma_f32_16x16x32_bf16 v[46:49], v[130:133], v[186:189], v[46:49]
	v_mfma_f32_16x16x32_bf16 v[42:45], v[138:141], v[186:189], v[42:45]
	v_mfma_f32_16x16x32_bf16 v[30:33], v[130:133], v[194:197], v[30:33]
	v_mfma_f32_16x16x32_bf16 v[26:29], v[138:141], v[194:197], v[26:29]
	v_mfma_f32_16x16x32_bf16 v[14:17], v[130:133], v[202:205], v[14:17]
	v_mfma_f32_16x16x32_bf16 v[10:13], v[138:141], v[202:205], v[10:13]
	v_mfma_f32_16x16x32_bf16 v[62:65], v[134:137], v[182:185], v[62:65]
	v_mfma_f32_16x16x32_bf16 v[58:61], v[142:145], v[182:185], v[58:61]
	v_mfma_f32_16x16x32_bf16 v[46:49], v[134:137], v[190:193], v[46:49]
	v_mfma_f32_16x16x32_bf16 v[42:45], v[142:145], v[190:193], v[42:45]
	v_mfma_f32_16x16x32_bf16 v[30:33], v[134:137], v[198:201], v[30:33]
	v_mfma_f32_16x16x32_bf16 v[26:29], v[142:145], v[198:201], v[26:29]
	v_mfma_f32_16x16x32_bf16 v[14:17], v[134:137], v[206:209], v[14:17]
	v_mfma_f32_16x16x32_bf16 v[10:13], v[142:145], v[206:209], v[10:13]
	v_mfma_f32_16x16x32_bf16 v[54:57], v[156:159], v[178:181], v[54:57]
	v_mfma_f32_16x16x32_bf16 v[50:53], v[170:173], v[178:181], v[50:53]
	v_mfma_f32_16x16x32_bf16 v[38:41], v[156:159], v[186:189], v[38:41]
	v_mfma_f32_16x16x32_bf16 v[34:37], v[170:173], v[186:189], v[34:37]
	v_mfma_f32_16x16x32_bf16 v[22:25], v[156:159], v[194:197], v[22:25]
	v_mfma_f32_16x16x32_bf16 v[18:21], v[170:173], v[194:197], v[18:21]
	v_mfma_f32_16x16x32_bf16 v[6:9], v[156:159], v[202:205], v[6:9]
	v_mfma_f32_16x16x32_bf16 v[2:5], v[170:173], v[202:205], v[2:5]
	v_mfma_f32_16x16x32_bf16 v[54:57], v[160:163], v[182:185], v[54:57]
	v_mfma_f32_16x16x32_bf16 v[50:53], v[174:177], v[182:185], v[50:53]
	v_mfma_f32_16x16x32_bf16 v[38:41], v[160:163], v[190:193], v[38:41]
	v_mfma_f32_16x16x32_bf16 v[34:37], v[174:177], v[190:193], v[34:37]
	v_mfma_f32_16x16x32_bf16 v[22:25], v[160:163], v[198:201], v[22:25]
	v_mfma_f32_16x16x32_bf16 v[18:21], v[174:177], v[198:201], v[18:21]
	v_mfma_f32_16x16x32_bf16 v[6:9], v[160:163], v[206:209], v[6:9]
	v_mfma_f32_16x16x32_bf16 v[2:5], v[174:177], v[206:209], v[2:5]
	s_barrier
	s_add_i32 s66, 0, 0x18000
	s_add_i32 s67, 0, 0x1c000
	v_add_u32_e32 v142, s66, v167
	v_add_u32_e32 v174, s67, v167
	ds_read_b128 v[130:133], v142
	ds_read_b128 v[134:137], v142 offset:1024
	ds_read_b128 v[138:141], v142 offset:2048
	ds_read_b128 v[142:145], v142 offset:3072
	ds_read_b128 v[156:159], v174
	ds_read_b128 v[160:163], v174 offset:1024
	ds_read_b128 v[170:173], v174 offset:2048
	ds_read_b128 v[174:177], v174 offset:3072
	s_add_u32 s50, s50, 0x200000
	s_addc_u32 s51, s51, 0
	s_mov_b32 m0, s54
	v_lshl_add_u64 v[222:223], s[50:51], 0, v[150:151]
	ds_read_b128 v[178:181], v169 offset:32768
	ds_read_b128 v[182:185], v169 offset:33792
	ds_read_b128 v[186:189], v169 offset:34816
	ds_read_b128 v[190:193], v169 offset:35840
	ds_read_b128 v[194:197], v169 offset:36864
	ds_read_b128 v[198:201], v169 offset:37888
	ds_read_b128 v[202:205], v169 offset:38912
	ds_read_b128 v[206:209], v169 offset:39936
	global_load_lds_dwordx4 v[222:223], off
	v_lshl_add_u64 v[222:223], s[50:51], 0, v[148:149]
	s_mov_b32 m0, s55
	s_nop 0
	global_load_lds_dwordx4 v[222:223], off
	s_waitcnt vmcnt(8)
	s_waitcnt lgkmcnt(0)
	s_barrier
	s_waitcnt lgkmcnt(0)
	v_mfma_f32_16x16x32_bf16 v[126:129], v[130:133], v[178:181], v[126:129]
	v_mfma_f32_16x16x32_bf16 v[122:125], v[138:141], v[178:181], v[122:125]
	v_mfma_f32_16x16x32_bf16 v[110:113], v[130:133], v[186:189], v[110:113]
	v_mfma_f32_16x16x32_bf16 v[106:109], v[138:141], v[186:189], v[106:109]
	v_mfma_f32_16x16x32_bf16 v[94:97], v[130:133], v[194:197], v[94:97]
	v_mfma_f32_16x16x32_bf16 v[90:93], v[138:141], v[194:197], v[90:93]
	v_mfma_f32_16x16x32_bf16 v[78:81], v[130:133], v[202:205], v[78:81]
	v_mfma_f32_16x16x32_bf16 v[74:77], v[138:141], v[202:205], v[74:77]
	v_mfma_f32_16x16x32_bf16 v[126:129], v[134:137], v[182:185], v[126:129]
	v_mfma_f32_16x16x32_bf16 v[122:125], v[142:145], v[182:185], v[122:125]
	v_mfma_f32_16x16x32_bf16 v[110:113], v[134:137], v[190:193], v[110:113]
	v_mfma_f32_16x16x32_bf16 v[106:109], v[142:145], v[190:193], v[106:109]
	v_mfma_f32_16x16x32_bf16 v[94:97], v[134:137], v[198:201], v[94:97]
	v_mfma_f32_16x16x32_bf16 v[90:93], v[142:145], v[198:201], v[90:93]
	v_mfma_f32_16x16x32_bf16 v[78:81], v[134:137], v[206:209], v[78:81]
	v_mfma_f32_16x16x32_bf16 v[74:77], v[142:145], v[206:209], v[74:77]
	v_mfma_f32_16x16x32_bf16 v[118:121], v[156:159], v[178:181], v[118:121]
	v_mfma_f32_16x16x32_bf16 v[114:117], v[170:173], v[178:181], v[114:117]
	v_mfma_f32_16x16x32_bf16 v[102:105], v[156:159], v[186:189], v[102:105]
	v_mfma_f32_16x16x32_bf16 v[98:101], v[170:173], v[186:189], v[98:101]
	v_mfma_f32_16x16x32_bf16 v[86:89], v[156:159], v[194:197], v[86:89]
	v_mfma_f32_16x16x32_bf16 v[82:85], v[170:173], v[194:197], v[82:85]
	v_mfma_f32_16x16x32_bf16 v[70:73], v[156:159], v[202:205], v[70:73]
	v_mfma_f32_16x16x32_bf16 v[66:69], v[170:173], v[202:205], v[66:69]
	v_mfma_f32_16x16x32_bf16 v[118:121], v[160:163], v[182:185], v[118:121]
	v_mfma_f32_16x16x32_bf16 v[114:117], v[174:177], v[182:185], v[114:117]
	v_mfma_f32_16x16x32_bf16 v[102:105], v[160:163], v[190:193], v[102:105]
	v_mfma_f32_16x16x32_bf16 v[98:101], v[174:177], v[190:193], v[98:101]
	v_mfma_f32_16x16x32_bf16 v[86:89], v[160:163], v[198:201], v[86:89]
	v_mfma_f32_16x16x32_bf16 v[82:85], v[174:177], v[198:201], v[82:85]
	v_mfma_f32_16x16x32_bf16 v[70:73], v[160:163], v[206:209], v[70:73]
	v_mfma_f32_16x16x32_bf16 v[66:69], v[174:177], v[206:209], v[66:69]
	s_barrier
	s_add_i32 s50, s66, s19
	v_lshl_add_u64 v[164:165], v[164:165], 0, s[22:23]
	s_mov_b32 m0, s50
	ds_read_b128 v[178:181], v169 offset:49152
	ds_read_b128 v[182:185], v169 offset:50176
	ds_read_b128 v[186:189], v169 offset:51200
	ds_read_b128 v[190:193], v169 offset:52224
	ds_read_b128 v[194:197], v169 offset:53248
	ds_read_b128 v[198:201], v169 offset:54272
	ds_read_b128 v[202:205], v169 offset:55296
	ds_read_b128 v[206:209], v169 offset:56320
	global_load_lds_dwordx4 v[164:165], off
	s_add_i32 m0, s50, 0x2000
	s_add_u32 s48, s48, 0x200080
	v_lshl_add_u64 v[164:165], v[216:217], 0, s[22:23]
	s_addc_u32 s49, s49, 0
	s_add_i32 s50, s67, s19
	global_load_lds_dwordx4 v[164:165], off
	v_lshl_add_u64 v[164:165], s[48:49], 0, v[0:1]
	s_mov_b32 m0, s50
	s_nop 0
	global_load_lds_dwordx4 v[164:165], off
	v_lshl_add_u64 v[164:165], s[48:49], 0, v[146:147]
	s_add_i32 m0, s50, 0x2000
	s_nop 0
	global_load_lds_dwordx4 v[164:165], off
	v_lshl_add_u64 v[164:165], v[218:219], 0, s[22:23]
	s_mov_b32 m0, s57
	s_nop 0
	global_load_lds_dwordx4 v[164:165], off
	v_lshl_add_u64 v[164:165], v[220:221], 0, s[22:23]
	s_mov_b32 m0, s58
	s_nop 0
	global_load_lds_dwordx4 v[164:165], off
	s_waitcnt vmcnt(8)
	s_waitcnt lgkmcnt(0)
	s_barrier
	s_waitcnt lgkmcnt(0)
	v_mfma_f32_16x16x32_bf16 v[62:65], v[130:133], v[178:181], v[62:65]
	v_mfma_f32_16x16x32_bf16 v[58:61], v[138:141], v[178:181], v[58:61]
	v_mfma_f32_16x16x32_bf16 v[46:49], v[130:133], v[186:189], v[46:49]
	v_mfma_f32_16x16x32_bf16 v[42:45], v[138:141], v[186:189], v[42:45]
	v_mfma_f32_16x16x32_bf16 v[30:33], v[130:133], v[194:197], v[30:33]
	v_mfma_f32_16x16x32_bf16 v[26:29], v[138:141], v[194:197], v[26:29]
	v_mfma_f32_16x16x32_bf16 v[14:17], v[130:133], v[202:205], v[14:17]
	v_mfma_f32_16x16x32_bf16 v[10:13], v[138:141], v[202:205], v[10:13]
	v_mfma_f32_16x16x32_bf16 v[62:65], v[134:137], v[182:185], v[62:65]
	v_mfma_f32_16x16x32_bf16 v[58:61], v[142:145], v[182:185], v[58:61]
	v_mfma_f32_16x16x32_bf16 v[46:49], v[134:137], v[190:193], v[46:49]
	v_mfma_f32_16x16x32_bf16 v[42:45], v[142:145], v[190:193], v[42:45]
	v_mfma_f32_16x16x32_bf16 v[30:33], v[134:137], v[198:201], v[30:33]
	v_mfma_f32_16x16x32_bf16 v[26:29], v[142:145], v[198:201], v[26:29]
	v_mfma_f32_16x16x32_bf16 v[14:17], v[134:137], v[206:209], v[14:17]
	v_mfma_f32_16x16x32_bf16 v[10:13], v[142:145], v[206:209], v[10:13]
	v_mfma_f32_16x16x32_bf16 v[54:57], v[156:159], v[178:181], v[54:57]
	v_mfma_f32_16x16x32_bf16 v[50:53], v[170:173], v[178:181], v[50:53]
	v_mfma_f32_16x16x32_bf16 v[38:41], v[156:159], v[186:189], v[38:41]
	v_mfma_f32_16x16x32_bf16 v[34:37], v[170:173], v[186:189], v[34:37]
	v_mfma_f32_16x16x32_bf16 v[22:25], v[156:159], v[194:197], v[22:25]
	v_mfma_f32_16x16x32_bf16 v[18:21], v[170:173], v[194:197], v[18:21]
	v_mfma_f32_16x16x32_bf16 v[6:9], v[156:159], v[202:205], v[6:9]
	v_mfma_f32_16x16x32_bf16 v[2:5], v[170:173], v[202:205], v[2:5]
	v_mfma_f32_16x16x32_bf16 v[54:57], v[160:163], v[182:185], v[54:57]
	v_mfma_f32_16x16x32_bf16 v[50:53], v[174:177], v[182:185], v[50:53]
	v_mfma_f32_16x16x32_bf16 v[38:41], v[160:163], v[190:193], v[38:41]
	v_mfma_f32_16x16x32_bf16 v[34:37], v[174:177], v[190:193], v[34:37]
	v_mfma_f32_16x16x32_bf16 v[22:25], v[160:163], v[198:201], v[22:25]
	v_mfma_f32_16x16x32_bf16 v[18:21], v[174:177], v[198:201], v[18:21]
	v_mfma_f32_16x16x32_bf16 v[6:9], v[160:163], v[206:209], v[6:9]
	v_mfma_f32_16x16x32_bf16 v[2:5], v[174:177], v[206:209], v[2:5]
	s_barrier
	s_add_i32 s65, s65, 2
	s_add_u32 s46, s46, 0x100
	s_addc_u32 s47, s47, 0
	s_add_u32 s63, s63, 0x100
	s_addc_u32 s64, s64, 0
	s_cmpk_gt_u32 s65, 0x7d
	s_cbranch_scc0 .LBB0_1763
	s_setprio 0
	s_and_b64 vcc, exec, s[8:9]
	s_cbranch_vccz .LBB0_1766
	s_barrier

.LBB0_1854:
	s_ashr_i32 s49, s48, 31
	s_lshl_b64 s[42:43], s[48:49], 20
	s_mov_b64 s[50:51], s[14:15]
	s_add_u32 s50, s50, s42
	s_addc_u32 s51, s51, s43
	s_and_b64 s[42:43], s[40:41], exec
	s_cselect_b32 s49, s51, s3
	s_cselect_b32 s55, s50, s2
	s_ashr_i32 s37, s36, 31
	s_lshl_b64 s[42:43], s[36:37], 20
	s_add_u32 s52, s17, s42
	s_addc_u32 s53, s18, s43
	s_and_b64 s[42:43], s[40:41], exec
	s_cselect_b32 s37, s53, s31
	s_cselect_b32 s64, s52, s30
	s_add_u32 s2, s2, 0x80080
	s_addc_u32 s3, s3, 0
	s_add_u32 s65, s30, 0x100
	v_mov_b32_e32 v2, 0
	s_addc_u32 s66, s31, 0
	s_mov_b32 s67, -2
	s_waitcnt lgkmcnt(0)
	v_mov_b32_e32 v3, v2
	v_mov_b32_e32 v4, v2
	v_mov_b32_e32 v5, v2
	v_mov_b32_e32 v6, v2
	v_mov_b32_e32 v7, v2
	v_mov_b32_e32 v8, v2
	v_mov_b32_e32 v9, v2
	v_mov_b32_e32 v18, v2
	v_mov_b32_e32 v19, v2
	v_mov_b32_e32 v20, v2
	v_mov_b32_e32 v21, v2
	v_mov_b32_e32 v22, v2
	v_mov_b32_e32 v23, v2
	v_mov_b32_e32 v24, v2
	v_mov_b32_e32 v25, v2
	v_mov_b32_e32 v34, v2
	v_mov_b32_e32 v35, v2
	v_mov_b32_e32 v36, v2
	v_mov_b32_e32 v37, v2
	v_mov_b32_e32 v38, v2
	v_mov_b32_e32 v39, v2
	v_mov_b32_e32 v40, v2
	v_mov_b32_e32 v41, v2
	v_mov_b32_e32 v50, v2
	v_mov_b32_e32 v51, v2
	v_mov_b32_e32 v52, v2
	v_mov_b32_e32 v53, v2
	v_mov_b32_e32 v54, v2
	v_mov_b32_e32 v55, v2
	v_mov_b32_e32 v56, v2
	v_mov_b32_e32 v57, v2
	v_mov_b32_e32 v10, v2
	v_mov_b32_e32 v11, v2
	v_mov_b32_e32 v12, v2
	v_mov_b32_e32 v13, v2
	v_mov_b32_e32 v14, v2
	v_mov_b32_e32 v15, v2
	v_mov_b32_e32 v16, v2
	v_mov_b32_e32 v17, v2
	v_mov_b32_e32 v26, v2
	v_mov_b32_e32 v27, v2
	v_mov_b32_e32 v28, v2
	v_mov_b32_e32 v29, v2
	v_mov_b32_e32 v30, v2
	v_mov_b32_e32 v31, v2
	v_mov_b32_e32 v32, v2
	v_mov_b32_e32 v33, v2
	v_mov_b32_e32 v42, v2
	v_mov_b32_e32 v43, v2
	v_mov_b32_e32 v44, v2
	v_mov_b32_e32 v45, v2
	v_mov_b32_e32 v46, v2
	v_mov_b32_e32 v47, v2
	v_mov_b32_e32 v48, v2
	v_mov_b32_e32 v49, v2
	v_mov_b32_e32 v58, v2
	v_mov_b32_e32 v59, v2
	v_mov_b32_e32 v60, v2
	v_mov_b32_e32 v61, v2
	v_mov_b32_e32 v62, v2
	v_mov_b32_e32 v63, v2
	v_mov_b32_e32 v64, v2
	v_mov_b32_e32 v65, v2
	v_mov_b32_e32 v66, v2
	v_mov_b32_e32 v67, v2
	v_mov_b32_e32 v68, v2
	v_mov_b32_e32 v69, v2
	v_mov_b32_e32 v70, v2
	v_mov_b32_e32 v71, v2
	v_mov_b32_e32 v72, v2
	v_mov_b32_e32 v73, v2
	v_mov_b32_e32 v82, v2
	v_mov_b32_e32 v83, v2
	v_mov_b32_e32 v84, v2
	v_mov_b32_e32 v85, v2
	v_mov_b32_e32 v86, v2
	v_mov_b32_e32 v87, v2
	v_mov_b32_e32 v88, v2
	v_mov_b32_e32 v89, v2
	v_mov_b32_e32 v98, v2
	v_mov_b32_e32 v99, v2
	v_mov_b32_e32 v100, v2
	v_mov_b32_e32 v101, v2
	v_mov_b32_e32 v102, v2
	v_mov_b32_e32 v103, v2
	v_mov_b32_e32 v104, v2
	v_mov_b32_e32 v105, v2
	v_mov_b32_e32 v114, v2
	v_mov_b32_e32 v115, v2
	v_mov_b32_e32 v116, v2
	v_mov_b32_e32 v117, v2
	v_mov_b32_e32 v118, v2
	v_mov_b32_e32 v119, v2
	v_mov_b32_e32 v120, v2
	v_mov_b32_e32 v121, v2
	v_mov_b32_e32 v74, v2
	v_mov_b32_e32 v75, v2
	v_mov_b32_e32 v76, v2
	v_mov_b32_e32 v77, v2
	v_mov_b32_e32 v78, v2
	v_mov_b32_e32 v79, v2
	v_mov_b32_e32 v80, v2
	v_mov_b32_e32 v81, v2
	v_mov_b32_e32 v90, v2
	v_mov_b32_e32 v91, v2
	v_mov_b32_e32 v92, v2
	v_mov_b32_e32 v93, v2
	v_mov_b32_e32 v94, v2
	v_mov_b32_e32 v95, v2
	v_mov_b32_e32 v96, v2
	v_mov_b32_e32 v97, v2
	v_mov_b32_e32 v106, v2
	v_mov_b32_e32 v107, v2
	v_mov_b32_e32 v108, v2
	v_mov_b32_e32 v109, v2
	v_mov_b32_e32 v110, v2
	v_mov_b32_e32 v111, v2
	v_mov_b32_e32 v112, v2
	v_mov_b32_e32 v113, v2
	v_mov_b32_e32 v122, v2
	v_mov_b32_e32 v123, v2
	v_mov_b32_e32 v124, v2
	v_mov_b32_e32 v125, v2
	v_mov_b32_e32 v126, v2
	v_mov_b32_e32 v127, v2
	v_mov_b32_e32 v128, v2
	v_mov_b32_e32 v129, v2
	v_readfirstlane_b32 s100, v211
	s_cmp_lt_u32 s100, 0x100
	s_cbranch_scc1 .Lpr_lead6
	s_setprio 1
.Lpr_lead6:
.LBB0_1855:
	s_add_u32 s30, s2, 0xfff80080
	s_addc_u32 s31, s3, -1
	s_add_i32 s68, 0, 0x10000
	s_cmp_eq_u32 s67, 28
	s_cselect_b32 s43, s49, s31
	s_cselect_b32 s42, s55, s30
	s_cselect_b32 s31, s37, s66
	s_cselect_b32 s30, s64, s65
	s_add_i32 s70, 0, 0x14000
	v_add_u32_e32 v142, s68, v241
	v_add_u32_e32 v170, s70, v241
	ds_read_b128 v[130:133], v142
	ds_read_b128 v[134:137], v142 offset:1024
	ds_read_b128 v[138:141], v142 offset:2048
	ds_read_b128 v[142:145], v142 offset:3072
	ds_read_b128 v[146:149], v170
	ds_read_b128 v[150:153], v170 offset:1024
	ds_read_b128 v[166:169], v170 offset:2048
	ds_read_b128 v[170:173], v170 offset:3072
	v_lshl_add_u64 v[206:207], s[2:3], 0, v[162:163]
	s_add_i32 m0, s56, 0xc000
	ds_read_b128 v[174:177], v243
	ds_read_b128 v[178:181], v243 offset:1024
	ds_read_b128 v[182:185], v243 offset:2048
	ds_read_b128 v[186:189], v243 offset:3072
	ds_read_b128 v[190:193], v243 offset:4096
	ds_read_b128 v[194:197], v243 offset:5120
	ds_read_b128 v[198:201], v243 offset:6144
	ds_read_b128 v[202:205], v243 offset:7168
	global_load_lds_dwordx4 v[206:207], off
	v_lshl_add_u64 v[206:207], s[2:3], 0, v[164:165]
	s_add_i32 m0, s56, 0xe000
	s_nop 0
	global_load_lds_dwordx4 v[206:207], off
	s_waitcnt vmcnt(8)
	s_waitcnt lgkmcnt(0)
	s_barrier
	s_waitcnt lgkmcnt(0)
	v_mfma_f32_16x16x32_bf16 v[126:129], v[130:133], v[174:177], v[126:129]
	v_mfma_f32_16x16x32_bf16 v[122:125], v[138:141], v[174:177], v[122:125]
	v_mfma_f32_16x16x32_bf16 v[110:113], v[130:133], v[182:185], v[110:113]
	v_mfma_f32_16x16x32_bf16 v[106:109], v[138:141], v[182:185], v[106:109]
	v_mfma_f32_16x16x32_bf16 v[94:97], v[130:133], v[190:193], v[94:97]
	v_mfma_f32_16x16x32_bf16 v[90:93], v[138:141], v[190:193], v[90:93]
	v_mfma_f32_16x16x32_bf16 v[78:81], v[130:133], v[198:201], v[78:81]
	v_mfma_f32_16x16x32_bf16 v[74:77], v[138:141], v[198:201], v[74:77]
	v_mfma_f32_16x16x32_bf16 v[126:129], v[134:137], v[178:181], v[126:129]
	v_mfma_f32_16x16x32_bf16 v[122:125], v[142:145], v[178:181], v[122:125]
	v_mfma_f32_16x16x32_bf16 v[110:113], v[134:137], v[186:189], v[110:113]
	v_mfma_f32_16x16x32_bf16 v[106:109], v[142:145], v[186:189], v[106:109]
	v_mfma_f32_16x16x32_bf16 v[94:97], v[134:137], v[194:197], v[94:97]
	v_mfma_f32_16x16x32_bf16 v[90:93], v[142:145], v[194:197], v[90:93]
	v_mfma_f32_16x16x32_bf16 v[78:81], v[134:137], v[202:205], v[78:81]
	v_mfma_f32_16x16x32_bf16 v[74:77], v[142:145], v[202:205], v[74:77]
	v_mfma_f32_16x16x32_bf16 v[118:121], v[146:149], v[174:177], v[118:121]
	v_mfma_f32_16x16x32_bf16 v[114:117], v[166:169], v[174:177], v[114:117]
	v_mfma_f32_16x16x32_bf16 v[102:105], v[146:149], v[182:185], v[102:105]
	v_mfma_f32_16x16x32_bf16 v[98:101], v[166:169], v[182:185], v[98:101]
	v_mfma_f32_16x16x32_bf16 v[86:89], v[146:149], v[190:193], v[86:89]
	v_mfma_f32_16x16x32_bf16 v[82:85], v[166:169], v[190:193], v[82:85]
	v_mfma_f32_16x16x32_bf16 v[70:73], v[146:149], v[198:201], v[70:73]
	v_mfma_f32_16x16x32_bf16 v[66:69], v[166:169], v[198:201], v[66:69]
	v_mfma_f32_16x16x32_bf16 v[118:121], v[150:153], v[178:181], v[118:121]
	v_mfma_f32_16x16x32_bf16 v[114:117], v[170:173], v[178:181], v[114:117]
	v_mfma_f32_16x16x32_bf16 v[102:105], v[150:153], v[186:189], v[102:105]
	v_mfma_f32_16x16x32_bf16 v[98:101], v[170:173], v[186:189], v[98:101]
	v_mfma_f32_16x16x32_bf16 v[86:89], v[150:153], v[194:197], v[86:89]
	v_mfma_f32_16x16x32_bf16 v[82:85], v[170:173], v[194:197], v[82:85]
	v_mfma_f32_16x16x32_bf16 v[70:73], v[150:153], v[202:205], v[70:73]
	v_mfma_f32_16x16x32_bf16 v[66:69], v[170:173], v[202:205], v[66:69]
	s_barrier
	s_add_i32 s68, s68, s19
	v_lshl_add_u64 v[206:207], s[30:31], 0, v[0:1]
	s_mov_b32 m0, s68
	ds_read_b128 v[174:177], v243 offset:16384
	ds_read_b128 v[178:181], v243 offset:17408
	ds_read_b128 v[182:185], v243 offset:18432
	ds_read_b128 v[186:189], v243 offset:19456
	ds_read_b128 v[190:193], v243 offset:20480
	ds_read_b128 v[194:197], v243 offset:21504
	ds_read_b128 v[198:201], v243 offset:22528
	ds_read_b128 v[202:205], v243 offset:23552
	global_load_lds_dwordx4 v[206:207], off
	s_add_i32 m0, s68, 0x2000
	s_add_u32 s68, s30, 0x80000
	v_lshl_add_u64 v[208:209], s[30:31], 0, v[154:155]
	s_addc_u32 s69, s31, 0
	s_add_i32 s70, s70, s19
	global_load_lds_dwordx4 v[208:209], off
	v_lshl_add_u64 v[216:217], s[68:69], 0, v[0:1]
	s_mov_b32 m0, s70
	v_lshl_add_u64 v[218:219], s[42:43], 0, v[156:157]
	global_load_lds_dwordx4 v[216:217], off
	v_lshl_add_u64 v[216:217], s[68:69], 0, v[154:155]
	s_add_i32 m0, s70, 0x2000
	s_nop 0
	global_load_lds_dwordx4 v[216:217], off
	v_lshl_add_u64 v[216:217], s[42:43], 0, v[158:159]
	s_mov_b32 m0, s56
	s_nop 0
	global_load_lds_dwordx4 v[216:217], off
	s_mov_b32 m0, s57
	s_nop 0
	global_load_lds_dwordx4 v[218:219], off
	s_waitcnt vmcnt(8)
	s_waitcnt lgkmcnt(0)
	s_barrier
	s_waitcnt lgkmcnt(0)
	v_mfma_f32_16x16x32_bf16 v[62:65], v[130:133], v[174:177], v[62:65]
	v_mfma_f32_16x16x32_bf16 v[58:61], v[138:141], v[174:177], v[58:61]
	v_mfma_f32_16x16x32_bf16 v[46:49], v[130:133], v[182:185], v[46:49]
	v_mfma_f32_16x16x32_bf16 v[42:45], v[138:141], v[182:185], v[42:45]
	v_mfma_f32_16x16x32_bf16 v[30:33], v[130:133], v[190:193], v[30:33]
	v_mfma_f32_16x16x32_bf16 v[26:29], v[138:141], v[190:193], v[26:29]
	v_mfma_f32_16x16x32_bf16 v[14:17], v[130:133], v[198:201], v[14:17]
	v_mfma_f32_16x16x32_bf16 v[10:13], v[138:141], v[198:201], v[10:13]
	v_mfma_f32_16x16x32_bf16 v[62:65], v[134:137], v[178:181], v[62:65]
	v_mfma_f32_16x16x32_bf16 v[58:61], v[142:145], v[178:181], v[58:61]
	v_mfma_f32_16x16x32_bf16 v[46:49], v[134:137], v[186:189], v[46:49]
	v_mfma_f32_16x16x32_bf16 v[42:45], v[142:145], v[186:189], v[42:45]
	v_mfma_f32_16x16x32_bf16 v[30:33], v[134:137], v[194:197], v[30:33]
	v_mfma_f32_16x16x32_bf16 v[26:29], v[142:145], v[194:197], v[26:29]
	v_mfma_f32_16x16x32_bf16 v[14:17], v[134:137], v[202:205], v[14:17]
	v_mfma_f32_16x16x32_bf16 v[10:13], v[142:145], v[202:205], v[10:13]
	v_mfma_f32_16x16x32_bf16 v[54:57], v[146:149], v[174:177], v[54:57]
	v_mfma_f32_16x16x32_bf16 v[50:53], v[166:169], v[174:177], v[50:53]
	v_mfma_f32_16x16x32_bf16 v[38:41], v[146:149], v[182:185], v[38:41]
	v_mfma_f32_16x16x32_bf16 v[34:37], v[166:169], v[182:185], v[34:37]
	v_mfma_f32_16x16x32_bf16 v[22:25], v[146:149], v[190:193], v[22:25]
	v_mfma_f32_16x16x32_bf16 v[18:21], v[166:169], v[190:193], v[18:21]
	v_mfma_f32_16x16x32_bf16 v[6:9], v[146:149], v[198:201], v[6:9]
	v_mfma_f32_16x16x32_bf16 v[2:5], v[166:169], v[198:201], v[2:5]
	v_mfma_f32_16x16x32_bf16 v[54:57], v[150:153], v[178:181], v[54:57]
	v_mfma_f32_16x16x32_bf16 v[50:53], v[170:173], v[178:181], v[50:53]
	v_mfma_f32_16x16x32_bf16 v[38:41], v[150:153], v[186:189], v[38:41]
	v_mfma_f32_16x16x32_bf16 v[34:37], v[170:173], v[186:189], v[34:37]
	v_mfma_f32_16x16x32_bf16 v[22:25], v[150:153], v[194:197], v[22:25]
	v_mfma_f32_16x16x32_bf16 v[18:21], v[170:173], v[194:197], v[18:21]
	v_mfma_f32_16x16x32_bf16 v[6:9], v[150:153], v[202:205], v[6:9]
	v_mfma_f32_16x16x32_bf16 v[2:5], v[170:173], v[202:205], v[2:5]
	s_barrier
	s_add_i32 s68, 0, 0x18000
	s_add_i32 s69, 0, 0x1c000
	v_add_u32_e32 v142, s68, v241
	v_add_u32_e32 v170, s69, v241
	ds_read_b128 v[130:133], v142
	ds_read_b128 v[134:137], v142 offset:1024
	ds_read_b128 v[138:141], v142 offset:2048
	ds_read_b128 v[142:145], v142 offset:3072
	ds_read_b128 v[146:149], v170
	ds_read_b128 v[150:153], v170 offset:1024
	ds_read_b128 v[166:169], v170 offset:2048
	ds_read_b128 v[170:173], v170 offset:3072
	s_add_u32 s42, s42, 0x80000
	s_addc_u32 s43, s43, 0
	s_mov_b32 m0, s58
	v_lshl_add_u64 v[220:221], s[42:43], 0, v[158:159]
	ds_read_b128 v[174:177], v243 offset:32768
	ds_read_b128 v[178:181], v243 offset:33792
	ds_read_b128 v[182:185], v243 offset:34816
	ds_read_b128 v[186:189], v243 offset:35840
	ds_read_b128 v[190:193], v243 offset:36864
	ds_read_b128 v[194:197], v243 offset:37888
	ds_read_b128 v[198:201], v243 offset:38912
	ds_read_b128 v[202:205], v243 offset:39936
	global_load_lds_dwordx4 v[220:221], off
	v_lshl_add_u64 v[220:221], s[42:43], 0, v[156:157]
	s_mov_b32 m0, s59
	s_nop 0
	global_load_lds_dwordx4 v[220:221], off
	s_waitcnt vmcnt(8)
	s_waitcnt lgkmcnt(0)
	s_barrier
	s_waitcnt lgkmcnt(0)
	v_mfma_f32_16x16x32_bf16 v[126:129], v[130:133], v[174:177], v[126:129]
	v_mfma_f32_16x16x32_bf16 v[122:125], v[138:141], v[174:177], v[122:125]
	v_mfma_f32_16x16x32_bf16 v[110:113], v[130:133], v[182:185], v[110:113]
	v_mfma_f32_16x16x32_bf16 v[106:109], v[138:141], v[182:185], v[106:109]
	v_mfma_f32_16x16x32_bf16 v[94:97], v[130:133], v[190:193], v[94:97]
	v_mfma_f32_16x16x32_bf16 v[90:93], v[138:141], v[190:193], v[90:93]
	v_mfma_f32_16x16x32_bf16 v[78:81], v[130:133], v[198:201], v[78:81]
	v_mfma_f32_16x16x32_bf16 v[74:77], v[138:141], v[198:201], v[74:77]
	v_mfma_f32_16x16x32_bf16 v[126:129], v[134:137], v[178:181], v[126:129]
	v_mfma_f32_16x16x32_bf16 v[122:125], v[142:145], v[178:181], v[122:125]
	v_mfma_f32_16x16x32_bf16 v[110:113], v[134:137], v[186:189], v[110:113]
	v_mfma_f32_16x16x32_bf16 v[106:109], v[142:145], v[186:189], v[106:109]
	v_mfma_f32_16x16x32_bf16 v[94:97], v[134:137], v[194:197], v[94:97]
	v_mfma_f32_16x16x32_bf16 v[90:93], v[142:145], v[194:197], v[90:93]
	v_mfma_f32_16x16x32_bf16 v[78:81], v[134:137], v[202:205], v[78:81]
	v_mfma_f32_16x16x32_bf16 v[74:77], v[142:145], v[202:205], v[74:77]
	v_mfma_f32_16x16x32_bf16 v[118:121], v[146:149], v[174:177], v[118:121]
	v_mfma_f32_16x16x32_bf16 v[114:117], v[166:169], v[174:177], v[114:117]
	v_mfma_f32_16x16x32_bf16 v[102:105], v[146:149], v[182:185], v[102:105]
	v_mfma_f32_16x16x32_bf16 v[98:101], v[166:169], v[182:185], v[98:101]
	v_mfma_f32_16x16x32_bf16 v[86:89], v[146:149], v[190:193], v[86:89]
	v_mfma_f32_16x16x32_bf16 v[82:85], v[166:169], v[190:193], v[82:85]
	v_mfma_f32_16x16x32_bf16 v[70:73], v[146:149], v[198:201], v[70:73]
	v_mfma_f32_16x16x32_bf16 v[66:69], v[166:169], v[198:201], v[66:69]
	v_mfma_f32_16x16x32_bf16 v[118:121], v[150:153], v[178:181], v[118:121]
	v_mfma_f32_16x16x32_bf16 v[114:117], v[170:173], v[178:181], v[114:117]
	v_mfma_f32_16x16x32_bf16 v[102:105], v[150:153], v[186:189], v[102:105]
	v_mfma_f32_16x16x32_bf16 v[98:101], v[170:173], v[186:189], v[98:101]
	v_mfma_f32_16x16x32_bf16 v[86:89], v[150:153], v[194:197], v[86:89]
	v_mfma_f32_16x16x32_bf16 v[82:85], v[170:173], v[194:197], v[82:85]
	v_mfma_f32_16x16x32_bf16 v[70:73], v[150:153], v[202:205], v[70:73]
	v_mfma_f32_16x16x32_bf16 v[66:69], v[170:173], v[202:205], v[66:69]
	s_barrier
	s_add_i32 s42, s68, s19
	v_lshl_add_u64 v[206:207], v[206:207], 0, s[22:23]
	s_mov_b32 m0, s42
	ds_read_b128 v[174:177], v243 offset:49152
	ds_read_b128 v[178:181], v243 offset:50176
	ds_read_b128 v[182:185], v243 offset:51200
	ds_read_b128 v[186:189], v243 offset:52224
	ds_read_b128 v[190:193], v243 offset:53248
	ds_read_b128 v[194:197], v243 offset:54272
	ds_read_b128 v[198:201], v243 offset:55296
	ds_read_b128 v[202:205], v243 offset:56320
	global_load_lds_dwordx4 v[206:207], off
	s_add_i32 m0, s42, 0x2000
	s_add_u32 s30, s30, 0x80080
	v_lshl_add_u64 v[206:207], v[208:209], 0, s[22:23]
	s_addc_u32 s31, s31, 0
	s_add_i32 s42, s69, s19
	global_load_lds_dwordx4 v[206:207], off
	v_lshl_add_u64 v[206:207], s[30:31], 0, v[0:1]
	s_mov_b32 m0, s42
	s_nop 0
	global_load_lds_dwordx4 v[206:207], off
	v_lshl_add_u64 v[206:207], s[30:31], 0, v[154:155]
	s_add_i32 m0, s42, 0x2000
	s_nop 0
	global_load_lds_dwordx4 v[206:207], off
	v_lshl_add_u64 v[206:207], v[216:217], 0, s[22:23]
	s_mov_b32 m0, s61
	s_nop 0
	global_load_lds_dwordx4 v[206:207], off
	v_lshl_add_u64 v[206:207], v[218:219], 0, s[22:23]
	s_mov_b32 m0, s62
	s_nop 0
	global_load_lds_dwordx4 v[206:207], off
	s_waitcnt vmcnt(8)
	s_waitcnt lgkmcnt(0)
	s_barrier
	s_waitcnt lgkmcnt(0)
	v_mfma_f32_16x16x32_bf16 v[62:65], v[130:133], v[174:177], v[62:65]
	v_mfma_f32_16x16x32_bf16 v[58:61], v[138:141], v[174:177], v[58:61]
	v_mfma_f32_16x16x32_bf16 v[46:49], v[130:133], v[182:185], v[46:49]
	v_mfma_f32_16x16x32_bf16 v[42:45], v[138:141], v[182:185], v[42:45]
	v_mfma_f32_16x16x32_bf16 v[30:33], v[130:133], v[190:193], v[30:33]
	v_mfma_f32_16x16x32_bf16 v[26:29], v[138:141], v[190:193], v[26:29]
	v_mfma_f32_16x16x32_bf16 v[14:17], v[130:133], v[198:201], v[14:17]
	v_mfma_f32_16x16x32_bf16 v[10:13], v[138:141], v[198:201], v[10:13]
	v_mfma_f32_16x16x32_bf16 v[62:65], v[134:137], v[178:181], v[62:65]
	v_mfma_f32_16x16x32_bf16 v[58:61], v[142:145], v[178:181], v[58:61]
	v_mfma_f32_16x16x32_bf16 v[46:49], v[134:137], v[186:189], v[46:49]
	v_mfma_f32_16x16x32_bf16 v[42:45], v[142:145], v[186:189], v[42:45]
	v_mfma_f32_16x16x32_bf16 v[30:33], v[134:137], v[194:197], v[30:33]
	v_mfma_f32_16x16x32_bf16 v[26:29], v[142:145], v[194:197], v[26:29]
	v_mfma_f32_16x16x32_bf16 v[14:17], v[134:137], v[202:205], v[14:17]
	v_mfma_f32_16x16x32_bf16 v[10:13], v[142:145], v[202:205], v[10:13]
	v_mfma_f32_16x16x32_bf16 v[54:57], v[146:149], v[174:177], v[54:57]
	v_mfma_f32_16x16x32_bf16 v[50:53], v[166:169], v[174:177], v[50:53]
	v_mfma_f32_16x16x32_bf16 v[38:41], v[146:149], v[182:185], v[38:41]
	v_mfma_f32_16x16x32_bf16 v[34:37], v[166:169], v[182:185], v[34:37]
	v_mfma_f32_16x16x32_bf16 v[22:25], v[146:149], v[190:193], v[22:25]
	v_mfma_f32_16x16x32_bf16 v[18:21], v[166:169], v[190:193], v[18:21]
	v_mfma_f32_16x16x32_bf16 v[6:9], v[146:149], v[198:201], v[6:9]
	v_mfma_f32_16x16x32_bf16 v[2:5], v[166:169], v[198:201], v[2:5]
	v_mfma_f32_16x16x32_bf16 v[54:57], v[150:153], v[178:181], v[54:57]
	v_mfma_f32_16x16x32_bf16 v[50:53], v[170:173], v[178:181], v[50:53]
	v_mfma_f32_16x16x32_bf16 v[38:41], v[150:153], v[186:189], v[38:41]
	v_mfma_f32_16x16x32_bf16 v[34:37], v[170:173], v[186:189], v[34:37]
	v_mfma_f32_16x16x32_bf16 v[22:25], v[150:153], v[194:197], v[22:25]
	v_mfma_f32_16x16x32_bf16 v[18:21], v[170:173], v[194:197], v[18:21]
	v_mfma_f32_16x16x32_bf16 v[6:9], v[150:153], v[202:205], v[6:9]
	v_mfma_f32_16x16x32_bf16 v[2:5], v[170:173], v[202:205], v[2:5]
	s_barrier
	s_add_i32 s67, s67, 2
	s_add_u32 s2, s2, 0x100
	s_addc_u32 s3, s3, 0
	s_add_u32 s65, s65, 0x100
	s_addc_u32 s66, s66, 0
	s_cmp_gt_u32 s67, 29
	s_cbranch_scc0 .LBB0_1855
	s_setprio 0
	s_and_b64 vcc, exec, s[46:47]
	s_cbranch_vccz .LBB0_1858
	s_barrier
